# v16: pass-epilogue store drains (vmcnt(0) before the closing barrier of each attention pass) removed so they overlap the next pass's cold Q/K/V loads
# baseline (speedup 1.0000x reference)
; __device__ __forceinline__ int crow(int r, int hi) { return (r & 3) + 8 * (r >> 2) + 4 * hi; }
; template <int MODE> ...
;     ...
;     __syncthreads();
;     constexpr float ONE_M_LI = 1.f - 0.35550906759f;
;     float sw[4];
; #pragma unroll
;     for (int d0 = 0; d0 < 4; ++d0) sw[d0] = subw[kh * 128 + d0 * 32 + r32] * ONE_M_LI;
;     char* zt = lds + wid * 8704;
; #pragma unroll
;     for (int r = 0; r < 16; ++r) { const int orow = crow(r, hi);
;       const float rstd = rsqrtf((L_lds[wid * 32 + orow] + L_lds[(wid ^ 1) * 32 + orow]) * (1.f / 256.f) + 1e-6f);
; #pragma unroll
;       for (int d0 = 0; d0 < 4; ++d0) { const float z = o[d0][r] * rstd * sw[d0];
;         *(unsigned short*)(zt + orow * 272 + (d0 * 32 + r32) * 2) = (unsigned short)(cvtpk(z, z) & 0xffffu); } }
.LBB0_1009:
	s_or_b64 exec, exec, s[26:27]
	v_lshlrev_b32_e32 v30, 7, v216
	v_or_b32_e32 v31, v30, v214
	v_readlane_b32 s84, v251, 0
	v_lshlrev_b32_e32 v31, 2, v31
	v_readlane_b32 s86, v251, 2
	v_readlane_b32 s87, v251, 3
	s_waitcnt lgkmcnt(0)
	s_barrier
	s_nop 2
	global_load_dword v45, v31, s[86:87]
	global_load_dword v46, v31, s[86:87] offset:128
	global_load_dword v48, v31, s[86:87] offset:256
	s_nop 0
	global_load_dword v31, v31, s[86:87] offset:384
	v_lshlrev_b32_e32 v49, 2, v213
	v_lshlrev_b32_e32 v50, 5, v215
	v_bitop3_b32 v44, v49, 32, v50 bitop3:0x36
	v_lshl_add_u32 v44, v44, 2, s25
	ds_read_b32 v47, v66
	ds_read_b32 v51, v44
	v_mul_lo_u32 v44, v215, s80
	v_add_u32_e32 v44, 0, v44
	v_lshl_add_u32 v65, v214, 1, v44
	v_or_b32_e32 v64, 1, v49
	s_waitcnt lgkmcnt(0)
	v_add_f32_e32 v47, v47, v51
	v_fmamk_f32 v47, v47, 0x3b800000, v209
	v_mul_f32_e32 v51, 0x4b800000, v47
	v_cmp_gt_f32_e32 vcc, s81, v47
	v_mad_u32_u24 v67, v213, s92, v65
	v_or_b32_e32 v49, v49, v50
	v_cndmask_b32_e32 v47, v47, v51, vcc
	v_rsq_f32_e32 v47, v47
	v_bitop3_b32 v51, v64, 32, v50 bitop3:0x36
	v_lshl_add_u32 v51, v51, 2, s25
	v_bitop3_b32 v50, v49, 32, 2 bitop3:0x36
	v_mul_f32_e32 v68, 0x45800000, v47
	v_cndmask_b32_e32 v47, v47, v68, vcc
	v_mul_f32_e32 v60, v60, v47
	v_mul_f32_e32 v68, v88, v47
	v_mul_f32_e32 v69, v92, v47
	v_mul_f32_e32 v70, v104, v47
	v_lshl_add_u32 v50, v50, 2, s25
	s_mul_i32 s2, s24, 0x4100
	s_mul_hi_i32 s3, s24, 0x4100
	s_add_u32 s2, s2, s22
	s_addc_u32 s3, s3, s23
	s_lshl_b64 s[2:3], s[2:3], 12
	s_add_u32 s24, s51, s2
	s_addc_u32 s26, s54, s3
	s_add_u32 s2, s44, s2
	s_addc_u32 s3, s45, s3
	v_lshlrev_b32_e32 v194, 1, v30
	v_readlane_b32 s85, v251, 1
	v_readlane_b32 s88, v251, 4
	v_readlane_b32 s89, v251, 5
	v_readlane_b32 s90, v251, 6
	v_readlane_b32 s91, v251, 7
	s_waitcnt vmcnt(3)
	v_mul_f32_e32 v47, 0x3f24fd5c, v45
	s_waitcnt vmcnt(2)
	v_mul_f32_e32 v46, 0x3f24fd5c, v46
	s_waitcnt vmcnt(1)
	v_mul_f32_e32 v45, 0x3f24fd5c, v48
	v_mul_f32_e32 v48, v47, v60
	v_cvt_pk_bf16_f32 v48, v48, v48
	v_mul_f32_e32 v60, v46, v68
	ds_write_b16 v67, v48
	v_cvt_pk_bf16_f32 v48, v60, v60
	s_waitcnt vmcnt(0)
	v_mul_f32_e32 v31, 0x3f24fd5c, v31
	v_mul_f32_e32 v68, v45, v69
	ds_write_b16 v67, v48 offset:64
	v_cvt_pk_bf16_f32 v48, v68, v68
	v_mul_f32_e32 v69, v31, v70
	ds_write_b16 v67, v48 offset:128
	v_cvt_pk_bf16_f32 v60, v69, v69
	ds_read_b32 v48, v66 offset:4
	ds_read_b32 v51, v51
	ds_write_b16 v67, v60 offset:192
	s_waitcnt lgkmcnt(1)
	v_add_f32_e32 v48, v48, v51
	v_fmamk_f32 v48, v48, 0x3b800000, v209
	v_mul_f32_e32 v51, 0x4b800000, v48
	v_cmp_gt_f32_e32 vcc, s81, v48
	s_nop 1
	v_cndmask_b32_e32 v48, v48, v51, vcc
	v_rsq_f32_e32 v51, v48
	v_mad_u32_u24 v48, v64, s93, v65
	v_mul_f32_e32 v60, 0x45800000, v51
	v_cndmask_b32_e32 v51, v51, v60, vcc
	v_mul_f32_e32 v60, v61, v51
	v_mul_f32_e32 v60, v47, v60
	v_mul_f32_e32 v61, v89, v51
	v_cvt_pk_bf16_f32 v60, v60, v60
	v_mul_f32_e32 v64, v93, v51
	v_mul_f32_e32 v51, v105, v51
	v_mul_f32_e32 v61, v46, v61
	ds_write_b16 v48, v60
	v_cvt_pk_bf16_f32 v60, v61, v61
	v_mul_f32_e32 v64, v45, v64
	v_mul_f32_e32 v51, v31, v51
	ds_write_b16 v48, v60 offset:64
	v_cvt_pk_bf16_f32 v60, v64, v64
	ds_write_b16 v48, v60 offset:128
	v_cvt_pk_bf16_f32 v51, v51, v51
	ds_read_b32 v60, v66 offset:8
	ds_read_b32 v50, v50
	ds_write_b16 v48, v51 offset:192
	s_waitcnt lgkmcnt(1)
	v_add_f32_e32 v50, v60, v50
	v_fmamk_f32 v50, v50, 0x3b800000, v209
	v_mul_f32_e32 v60, 0x4b800000, v50
	v_cmp_gt_f32_e32 vcc, s81, v50
	s_nop 1
	v_cndmask_b32_e32 v50, v50, v60, vcc
	v_rsq_f32_e32 v50, v50
	v_bitop3_b32 v60, v49, 32, 3 bitop3:0x36
	v_lshl_add_u32 v60, v60, 2, s25
	v_mul_f32_e32 v51, 0x45800000, v50
	v_cndmask_b32_e32 v50, v50, v51, vcc
	v_mul_f32_e32 v32, v32, v50
	v_mul_f32_e32 v32, v47, v32
	v_mul_f32_e32 v34, v34, v50
	v_cvt_pk_bf16_f32 v32, v32, v32
	v_mul_f32_e32 v51, v62, v50
	v_mul_f32_e32 v50, v90, v50
	v_mul_f32_e32 v34, v46, v34
	ds_write_b16 v48, v32 offset:272
	v_cvt_pk_bf16_f32 v32, v34, v34
	v_mul_f32_e32 v51, v45, v51
	v_mul_f32_e32 v50, v31, v50
	ds_write_b16 v48, v32 offset:336
	v_cvt_pk_bf16_f32 v32, v51, v51
	ds_write_b16 v48, v32 offset:400
	v_cvt_pk_bf16_f32 v32, v50, v50
	ds_read_b32 v34, v66 offset:12
	ds_read_b32 v50, v60
	ds_write_b16 v48, v32 offset:464
	s_waitcnt lgkmcnt(1)
	v_add_f32_e32 v34, v34, v50
	v_fmamk_f32 v34, v34, 0x3b800000, v209
	v_mul_f32_e32 v50, 0x4b800000, v34
	v_cmp_gt_f32_e32 vcc, s81, v34
	s_nop 1
	v_cndmask_b32_e32 v34, v34, v50, vcc
	v_rsq_f32_e32 v34, v34
	v_bitop3_b32 v50, v49, 32, 8 bitop3:0x36
	v_lshl_add_u32 v50, v50, 2, s25
	v_mul_f32_e32 v32, 0x45800000, v34
	v_cndmask_b32_e32 v32, v34, v32, vcc
	v_mul_f32_e32 v33, v33, v32
	v_mul_f32_e32 v33, v47, v33
	v_mul_f32_e32 v34, v35, v32
	v_cvt_pk_bf16_f32 v33, v33, v33
	v_mul_f32_e32 v35, v63, v32
	v_mul_f32_e32 v32, v91, v32
	v_mul_f32_e32 v34, v46, v34
	ds_write_b16 v48, v33 offset:544
	v_cvt_pk_bf16_f32 v33, v34, v34
	v_mul_f32_e32 v35, v45, v35
	v_mul_f32_e32 v32, v31, v32
	ds_write_b16 v48, v33 offset:608
	v_cvt_pk_bf16_f32 v33, v35, v35
	ds_write_b16 v48, v33 offset:672
	v_cvt_pk_bf16_f32 v32, v32, v32
	ds_read_b32 v33, v66 offset:32
	ds_read_b32 v34, v50
	ds_write_b16 v48, v32 offset:736
	s_waitcnt lgkmcnt(1)
; __device__ __forceinline__ int crow(int r, int hi) { return (r & 3) + 8 * (r >> 2) + 4 * hi; }
; template <int MODE> ...
;     ...
; #pragma unroll
;     for (int r = 0; r < 16; ++r) { const int orow = crow(r, hi);
;       const float rstd = rsqrtf((L_lds[wid * 32 + orow] + L_lds[(wid ^ 1) * 32 + orow]) * (1.f / 256.f) + 1e-6f);
; #pragma unroll
;       for (int d0 = 0; d0 < 4; ++d0) { const float z = o[d0][r] * rstd * sw[d0];
;         *(unsigned short*)(zt + orow * 272 + (d0 * 32 + r32) * 2) = (unsigned short)(cvtpk(z, z) & 0xffffu); } }
	v_add_f32_e32 v33, v33, v34
	v_fmamk_f32 v33, v33, 0x3b800000, v209
	v_mul_f32_e32 v34, 0x4b800000, v33
	v_cmp_gt_f32_e32 vcc, s81, v33
	s_nop 1
	v_cndmask_b32_e32 v33, v33, v34, vcc
	v_rsq_f32_e32 v33, v33
	v_bitop3_b32 v34, v49, 32, 9 bitop3:0x36
	v_lshl_add_u32 v34, v34, 2, s25
	v_mul_f32_e32 v32, 0x45800000, v33
	v_cndmask_b32_e32 v32, v33, v32, vcc
	v_mul_f32_e32 v4, v4, v32
	v_mul_f32_e32 v2, v2, v32
	v_mul_f32_e32 v0, v0, v32
	v_mul_f32_e32 v4, v47, v4
	v_mul_f32_e32 v2, v46, v2
	v_mul_f32_e32 v0, v45, v0
	v_mul_f32_e32 v32, v36, v32
	v_cvt_pk_bf16_f32 v4, v4, v4
	ds_write_b16 v48, v4 offset:1904
	v_cvt_pk_bf16_f32 v2, v2, v2
	ds_write_b16 v48, v2 offset:1968
	v_cvt_pk_bf16_f32 v0, v0, v0
	v_mul_f32_e32 v32, v31, v32
	ds_write_b16 v48, v0 offset:2032
	v_cvt_pk_bf16_f32 v0, v32, v32
	ds_read_b32 v2, v66 offset:36
	ds_read_b32 v4, v34
	ds_write_b16 v48, v0 offset:2096
	s_waitcnt lgkmcnt(1)
	v_add_f32_e32 v2, v2, v4
	v_fmamk_f32 v2, v2, 0x3b800000, v209
	v_mul_f32_e32 v4, 0x4b800000, v2
	v_cmp_gt_f32_e32 vcc, s81, v2
	s_nop 1
	v_cndmask_b32_e32 v2, v2, v4, vcc
	v_rsq_f32_e32 v2, v2
	s_nop 0
	v_mul_f32_e32 v0, 0x45800000, v2
	v_cndmask_b32_e32 v0, v2, v0, vcc
	v_mul_f32_e32 v2, v5, v0
	v_mul_f32_e32 v1, v1, v0
	v_mul_f32_e32 v2, v47, v2
	v_mul_f32_e32 v3, v3, v0
	v_mul_f32_e32 v1, v45, v1
	v_cvt_pk_bf16_f32 v2, v2, v2
	v_mul_f32_e32 v3, v46, v3
	ds_write_b16 v48, v2 offset:2176
	v_cvt_pk_bf16_f32 v2, v3, v3
	ds_write_b16 v48, v2 offset:2240
	v_cvt_pk_bf16_f32 v1, v1, v1
	v_mul_f32_e32 v0, v37, v0
	ds_write_b16 v48, v1 offset:2304
	v_bitop3_b32 v1, v49, 32, 10 bitop3:0x36
	v_mul_f32_e32 v0, v31, v0
	v_lshl_add_u32 v1, v1, 2, s25
	v_cvt_pk_bf16_f32 v0, v0, v0
	ds_read_b32 v2, v66 offset:40
	ds_read_b32 v1, v1
	ds_write_b16 v48, v0 offset:2368
	v_mov_b32_e32 v3, v195
	s_waitcnt lgkmcnt(1)
	v_add_f32_e32 v1, v2, v1
	v_fmamk_f32 v1, v1, 0x3b800000, v209
	v_mul_f32_e32 v2, 0x4b800000, v1
	v_cmp_gt_f32_e32 vcc, s81, v1
	s_nop 1
	v_cndmask_b32_e32 v1, v1, v2, vcc
	v_rsq_f32_e32 v1, v1
	s_nop 0
	v_mul_f32_e32 v0, 0x45800000, v1
	v_cndmask_b32_e32 v0, v1, v0, vcc
	v_mul_f32_e32 v1, v18, v0
	v_mul_f32_e32 v1, v47, v1
	v_cvt_pk_bf16_f32 v1, v1, v1
	ds_write_b16 v48, v1 offset:2448
	v_mul_f32_e32 v1, v16, v0
	v_mul_f32_e32 v1, v46, v1
	v_cvt_pk_bf16_f32 v1, v1, v1
	ds_write_b16 v48, v1 offset:2512
	v_mul_f32_e32 v1, v20, v0
	v_mul_f32_e32 v1, v45, v1
	v_cvt_pk_bf16_f32 v1, v1, v1
	ds_write_b16 v48, v1 offset:2576
	v_mul_f32_e32 v0, v6, v0
	v_bitop3_b32 v1, v49, 32, 11 bitop3:0x36
	v_mul_f32_e32 v0, v31, v0
	v_lshl_add_u32 v1, v1, 2, s25
	v_cvt_pk_bf16_f32 v0, v0, v0
	ds_read_b32 v2, v66 offset:44
	ds_read_b32 v1, v1
	ds_write_b16 v48, v0 offset:2640
	s_waitcnt lgkmcnt(1)
	v_add_f32_e32 v1, v2, v1
	v_fmamk_f32 v1, v1, 0x3b800000, v209
	v_mul_f32_e32 v2, 0x4b800000, v1
	v_cmp_gt_f32_e32 vcc, s81, v1
	s_nop 1
	v_cndmask_b32_e32 v1, v1, v2, vcc
	v_rsq_f32_e32 v1, v1
	s_nop 0
	v_mul_f32_e32 v0, 0x45800000, v1
	v_cndmask_b32_e32 v0, v1, v0, vcc
	v_mul_f32_e32 v1, v19, v0
	v_mul_f32_e32 v1, v47, v1
	v_cvt_pk_bf16_f32 v1, v1, v1
	ds_write_b16 v48, v1 offset:2720
	v_mul_f32_e32 v1, v17, v0
	v_mul_f32_e32 v1, v46, v1
	v_cvt_pk_bf16_f32 v1, v1, v1
	ds_write_b16 v48, v1 offset:2784
	v_mul_f32_e32 v1, v21, v0
	v_mul_f32_e32 v1, v45, v1
	v_cvt_pk_bf16_f32 v1, v1, v1
	ds_write_b16 v48, v1 offset:2848
	v_mul_f32_e32 v0, v7, v0
	v_bitop3_b32 v1, v49, 32, 16 bitop3:0x36
	v_mul_f32_e32 v0, v31, v0
	v_lshl_add_u32 v1, v1, 2, s25
	v_cvt_pk_bf16_f32 v0, v0, v0
	ds_read_b32 v2, v66 offset:64
	ds_read_b32 v1, v1
	ds_write_b16 v48, v0 offset:2912
	s_waitcnt lgkmcnt(1)
	v_add_f32_e32 v1, v2, v1
	v_fmamk_f32 v1, v1, 0x3b800000, v209
	v_mul_f32_e32 v2, 0x4b800000, v1
	v_cmp_gt_f32_e32 vcc, s81, v1
	s_nop 1
	v_cndmask_b32_e32 v1, v1, v2, vcc
	v_rsq_f32_e32 v1, v1
	s_nop 0
	v_mul_f32_e32 v0, 0x45800000, v1
	v_cndmask_b32_e32 v0, v1, v0, vcc
	v_mul_f32_e32 v1, v22, v0
	v_mul_f32_e32 v1, v47, v1
	v_cvt_pk_bf16_f32 v1, v1, v1
	ds_write_b16 v48, v1 offset:4080
	v_mul_f32_e32 v1, v8, v0
	v_mul_f32_e32 v1, v46, v1
	v_cvt_pk_bf16_f32 v1, v1, v1
	ds_write_b16 v48, v1 offset:4144
	v_mul_f32_e32 v1, v58, v0
	v_mul_f32_e32 v1, v45, v1
	v_cvt_pk_bf16_f32 v1, v1, v1
	ds_write_b16 v48, v1 offset:4208
	v_mul_f32_e32 v0, v72, v0
	v_bitop3_b32 v1, v49, 32, 17 bitop3:0x36
	v_mul_f32_e32 v0, v31, v0
	v_lshl_add_u32 v1, v1, 2, s25
	v_cvt_pk_bf16_f32 v0, v0, v0
	ds_read_b32 v2, v66 offset:68
	ds_read_b32 v1, v1
	ds_write_b16 v48, v0 offset:4272
	s_waitcnt lgkmcnt(1)
	v_add_f32_e32 v1, v2, v1
	v_fmamk_f32 v1, v1, 0x3b800000, v209
	v_mul_f32_e32 v2, 0x4b800000, v1
	v_cmp_gt_f32_e32 vcc, s81, v1
	s_nop 1
	v_cndmask_b32_e32 v1, v1, v2, vcc
	v_rsq_f32_e32 v1, v1
	s_nop 0
	v_mul_f32_e32 v0, 0x45800000, v1
	v_cndmask_b32_e32 v0, v1, v0, vcc
	v_mul_f32_e32 v1, v23, v0
	v_mul_f32_e32 v1, v47, v1
	v_cvt_pk_bf16_f32 v1, v1, v1
	ds_write_b16 v48, v1 offset:4352
	v_mul_f32_e32 v1, v9, v0
	v_mul_f32_e32 v1, v46, v1
	v_cvt_pk_bf16_f32 v1, v1, v1
	ds_write_b16 v48, v1 offset:4416
	v_mul_f32_e32 v1, v59, v0
	v_mul_f32_e32 v1, v45, v1
	v_cvt_pk_bf16_f32 v1, v1, v1
	ds_write_b16 v48, v1 offset:4480
	v_mul_f32_e32 v0, v73, v0
	v_bitop3_b32 v1, v49, 32, 18 bitop3:0x36
	v_mul_f32_e32 v0, v31, v0
	v_lshl_add_u32 v1, v1, 2, s25
	v_cvt_pk_bf16_f32 v0, v0, v0
	ds_read_b32 v2, v66 offset:72
	ds_read_b32 v1, v1
	ds_write_b16 v48, v0 offset:4544
	s_waitcnt lgkmcnt(1)
; __device__ __forceinline__ int crow(int r, int hi) { return (r & 3) + 8 * (r >> 2) + 4 * hi; }
; template <int MODE> ...
;     ...
; #pragma unroll
;     for (int r = 0; r < 16; ++r) { const int orow = crow(r, hi);
;       const float rstd = rsqrtf((L_lds[wid * 32 + orow] + L_lds[(wid ^ 1) * 32 + orow]) * (1.f / 256.f) + 1e-6f);
; #pragma unroll
;       for (int d0 = 0; d0 < 4; ++d0) { const float z = o[d0][r] * rstd * sw[d0];
;         *(unsigned short*)(zt + orow * 272 + (d0 * 32 + r32) * 2) = (unsigned short)(cvtpk(z, z) & 0xffffu); } }
;     asm volatile("s_waitcnt lgkmcnt(0)" ::: "memory");
;     u32x4 gq[8];
; #pragma unroll
;     for (int i = 0; i < 8; ++i) { const int id = lane + 64 * i; gq[i] = *(const u32x4*)(Gw + (long)(g * 32 + (id >> 4)) * 2048 + kh * 128 + (id & 15) * 8); }
	v_add_f32_e32 v1, v2, v1
	v_fmamk_f32 v1, v1, 0x3b800000, v209
	v_mul_f32_e32 v2, 0x4b800000, v1
	v_cmp_gt_f32_e32 vcc, s81, v1
	s_nop 1
	v_cndmask_b32_e32 v1, v1, v2, vcc
	v_rsq_f32_e32 v1, v1
	s_nop 0
	v_mul_f32_e32 v0, 0x45800000, v1
	v_cndmask_b32_e32 v0, v1, v0, vcc
	v_mul_f32_e32 v1, v56, v0
	v_mul_f32_e32 v1, v47, v1
	v_cvt_pk_bf16_f32 v1, v1, v1
	ds_write_b16 v48, v1 offset:4624
	v_mul_f32_e32 v1, v54, v0
	v_mul_f32_e32 v1, v46, v1
	v_cvt_pk_bf16_f32 v1, v1, v1
	ds_write_b16 v48, v1 offset:4688
	v_mul_f32_e32 v1, v52, v0
	v_mul_f32_e32 v1, v45, v1
	v_cvt_pk_bf16_f32 v1, v1, v1
	ds_write_b16 v48, v1 offset:4752
	v_mul_f32_e32 v0, v42, v0
	v_bitop3_b32 v1, v49, 32, 19 bitop3:0x36
	v_mul_f32_e32 v0, v31, v0
	v_lshl_add_u32 v1, v1, 2, s25
	v_cvt_pk_bf16_f32 v0, v0, v0
	ds_read_b32 v2, v66 offset:76
	ds_read_b32 v1, v1
	ds_write_b16 v48, v0 offset:4816
	s_waitcnt lgkmcnt(1)
	v_add_f32_e32 v1, v2, v1
	v_fmamk_f32 v1, v1, 0x3b800000, v209
	v_mul_f32_e32 v2, 0x4b800000, v1
	v_cmp_gt_f32_e32 vcc, s81, v1
	s_nop 1
	v_cndmask_b32_e32 v1, v1, v2, vcc
	v_rsq_f32_e32 v1, v1
	s_nop 0
	v_mul_f32_e32 v0, 0x45800000, v1
	v_cndmask_b32_e32 v0, v1, v0, vcc
	v_mul_f32_e32 v1, v57, v0
	v_mul_f32_e32 v1, v47, v1
	v_cvt_pk_bf16_f32 v1, v1, v1
	ds_write_b16 v48, v1 offset:4896
	v_mul_f32_e32 v1, v55, v0
	v_mul_f32_e32 v1, v46, v1
	v_cvt_pk_bf16_f32 v1, v1, v1
	ds_write_b16 v48, v1 offset:4960
	v_mul_f32_e32 v1, v53, v0
	v_mul_f32_e32 v1, v45, v1
	v_cvt_pk_bf16_f32 v1, v1, v1
	ds_write_b16 v48, v1 offset:5024
	v_mul_f32_e32 v0, v43, v0
	v_bitop3_b32 v1, v49, 32, 24 bitop3:0x36
	v_mul_f32_e32 v0, v31, v0
	v_lshl_add_u32 v1, v1, 2, s25
	v_cvt_pk_bf16_f32 v0, v0, v0
	ds_read_b32 v2, v66 offset:96
	ds_read_b32 v1, v1
	ds_write_b16 v48, v0 offset:5088
	s_waitcnt lgkmcnt(1)
	v_add_f32_e32 v1, v2, v1
	v_fmamk_f32 v1, v1, 0x3b800000, v209
	v_mul_f32_e32 v2, 0x4b800000, v1
	v_cmp_gt_f32_e32 vcc, s81, v1
	s_nop 1
	v_cndmask_b32_e32 v1, v1, v2, vcc
	v_rsq_f32_e32 v1, v1
	s_nop 0
	v_mul_f32_e32 v0, 0x45800000, v1
	v_cndmask_b32_e32 v0, v1, v0, vcc
	v_mul_f32_e32 v1, v40, v0
	v_mul_f32_e32 v1, v47, v1
	v_cvt_pk_bf16_f32 v1, v1, v1
	ds_write_b16 v48, v1 offset:6256
	v_mul_f32_e32 v1, v38, v0
	v_mul_f32_e32 v1, v46, v1
	v_cvt_pk_bf16_f32 v1, v1, v1
	ds_write_b16 v48, v1 offset:6320
	v_mul_f32_e32 v1, v28, v0
	v_mul_f32_e32 v1, v45, v1
	v_cvt_pk_bf16_f32 v1, v1, v1
	ds_write_b16 v48, v1 offset:6384
	v_mul_f32_e32 v0, v26, v0
	v_bitop3_b32 v1, v49, 32, 25 bitop3:0x36
	v_mul_f32_e32 v0, v31, v0
	v_lshl_add_u32 v1, v1, 2, s25
	v_cvt_pk_bf16_f32 v0, v0, v0
	ds_read_b32 v2, v66 offset:100
	ds_read_b32 v1, v1
	ds_write_b16 v48, v0 offset:6448
	v_lshlrev_b32_e32 v38, 4, v211
	s_waitcnt lgkmcnt(1)
	v_add_f32_e32 v1, v2, v1
	v_fmamk_f32 v1, v1, 0x3b800000, v209
	v_mul_f32_e32 v2, 0x4b800000, v1
	v_cmp_gt_f32_e32 vcc, s81, v1
	s_nop 1
	v_cndmask_b32_e32 v1, v1, v2, vcc
	v_rsq_f32_e32 v1, v1
	s_nop 0
	v_mul_f32_e32 v0, 0x45800000, v1
	v_cndmask_b32_e32 v0, v1, v0, vcc
	v_mul_f32_e32 v1, v41, v0
	v_mul_f32_e32 v1, v47, v1
	v_cvt_pk_bf16_f32 v1, v1, v1
	ds_write_b16 v48, v1 offset:6528
	v_mul_f32_e32 v1, v39, v0
	v_mul_f32_e32 v1, v46, v1
	v_cvt_pk_bf16_f32 v1, v1, v1
	ds_write_b16 v48, v1 offset:6592
	v_mul_f32_e32 v1, v29, v0
	v_mul_f32_e32 v1, v45, v1
	v_cvt_pk_bf16_f32 v1, v1, v1
	ds_write_b16 v48, v1 offset:6656
	v_mul_f32_e32 v0, v27, v0
	v_bitop3_b32 v1, v49, 32, 26 bitop3:0x36
	v_mul_f32_e32 v0, v31, v0
	v_lshl_add_u32 v1, v1, 2, s25
	v_cvt_pk_bf16_f32 v0, v0, v0
	ds_read_b32 v2, v66 offset:104
	ds_read_b32 v1, v1
	ds_write_b16 v48, v0 offset:6720
	v_mov_b32_e32 v39, v195
	s_waitcnt lgkmcnt(1)
	v_add_f32_e32 v1, v2, v1
	v_fmamk_f32 v1, v1, 0x3b800000, v209
	v_mul_f32_e32 v2, 0x4b800000, v1
	v_cmp_gt_f32_e32 vcc, s81, v1
	s_nop 1
	v_cndmask_b32_e32 v1, v1, v2, vcc
	v_rsq_f32_e32 v1, v1
	s_nop 0
	v_mul_f32_e32 v0, 0x45800000, v1
	v_cndmask_b32_e32 v0, v1, v0, vcc
	v_mul_f32_e32 v1, v12, v0
	v_mul_f32_e32 v1, v47, v1
	v_cvt_pk_bf16_f32 v1, v1, v1
	ds_write_b16 v48, v1 offset:6800
	v_mul_f32_e32 v1, v10, v0
	v_mul_f32_e32 v1, v46, v1
	v_cvt_pk_bf16_f32 v1, v1, v1
	ds_write_b16 v48, v1 offset:6864
	v_mul_f32_e32 v1, v14, v0
	v_mul_f32_e32 v1, v45, v1
	v_cvt_pk_bf16_f32 v1, v1, v1
	ds_write_b16 v48, v1 offset:6928
	v_mul_f32_e32 v0, v24, v0
	v_bitop3_b32 v1, v49, 32, 27 bitop3:0x36
	v_mul_f32_e32 v0, v31, v0
	v_lshl_add_u32 v1, v1, 2, s25
	v_cvt_pk_bf16_f32 v0, v0, v0
	ds_read_b32 v2, v66 offset:108
	ds_read_b32 v1, v1
	ds_write_b16 v48, v0 offset:6992
	s_lshl_b32 s25, s94, 1
	s_add_u32 s22, s2, s25
	s_addc_u32 s23, s3, 0
	s_waitcnt lgkmcnt(1)
	v_add_f32_e32 v1, v2, v1
	v_fmamk_f32 v1, v1, 0x3b800000, v209
	v_mul_f32_e32 v2, 0x4b800000, v1
	v_cmp_gt_f32_e32 vcc, s81, v1
	s_add_u32 s2, s24, s25
	s_addc_u32 s3, s26, 0
	v_cndmask_b32_e32 v1, v1, v2, vcc
	v_rsq_f32_e32 v1, v1
	v_and_b32_e32 v2, 0x78, v212
	v_lshlrev_b32_e32 v2, 1, v2
	v_lshl_add_u64 v[26:27], s[22:23], 0, v[194:195]
	v_mul_f32_e32 v0, 0x45800000, v1
	v_cndmask_b32_e32 v0, v1, v0, vcc
	v_mul_f32_e32 v1, v13, v0
	v_mul_f32_e32 v1, v47, v1
	v_cvt_pk_bf16_f32 v1, v1, v1
	ds_write_b16 v48, v1 offset:7072
	v_mul_f32_e32 v1, v11, v0
	v_mul_f32_e32 v1, v46, v1
	v_cvt_pk_bf16_f32 v1, v1, v1
	ds_write_b16 v48, v1 offset:7136
	v_mul_f32_e32 v1, v15, v0
	v_mul_f32_e32 v0, v25, v0
	v_mul_f32_e32 v1, v45, v1
	v_mul_f32_e32 v0, v31, v0
	v_cvt_pk_bf16_f32 v1, v1, v1
	ds_write_b16 v48, v1 offset:7200
	v_cvt_pk_bf16_f32 v0, v0, v0
	ds_write_b16 v48, v0 offset:7264
	v_lshl_add_u64 v[0:1], s[2:3], 0, v[194:195]
	v_lshl_add_u64 v[0:1], v[0:1], 0, v[2:3]
	v_or_b32_e32 v2, v199, v196
	v_ashrrev_i32_e32 v3, 31, v2
	v_lshlrev_b64 v[54:55], 12, v[2:3]
	s_waitcnt lgkmcnt(0)
; template <int MODE> ...
;     ...
;     u32x4 gq[8];
; #pragma unroll
;     for (int i = 0; i < 8; ++i) { const int id = lane + 64 * i; gq[i] = *(const u32x4*)(Gw + (long)(g * 32 + (id >> 4)) * 2048 + kh * 128 + (id & 15) * 8); }
; #pragma unroll
;     for (int i = 0; i < 8; ++i) { const int id = lane + 64 * i, row = id >> 4, cc = id & 15;
;       const u32x4 zz = *(const u32x4*)(zt + row * 272 + cc * 16);
;       unsigned yo[4];
; #pragma unroll
;       for (int k = 0; k < 4; ++k) { const unsigned zw = zz[k], gw_ = gq[i][k];
;         const float z0 = __builtin_bit_cast(float, zw << 16), z1 = __builtin_bit_cast(float, zw & 0xffff0000u);
;         const float g0 = __builtin_bit_cast(float, gw_ << 16), g1 = __builtin_bit_cast(float, gw_ & 0xffff0000u);
;         yo[k] = cvtpk(z0 * (g0 * __builtin_amdgcn_rcpf(1.f + __expf(-g0))), z1 * (g1 * __builtin_amdgcn_rcpf(1.f + __expf(-g1)))); }
;       *(u32x4*)(A2w + (long)(g * 32 + row) * 2048 + kh * 128 + cc * 8) = (u32x4){yo[0], yo[1], yo[2], yo[3]}; }
	v_lshl_add_u64 v[4:5], v[0:1], 0, v[54:55]
	global_load_dwordx4 v[40:43], v[4:5], off
	v_or_b32_e32 v4, 4, v2
	v_ashrrev_i32_e32 v5, 31, v4
	v_lshlrev_b64 v[56:57], 12, v[4:5]
	v_lshl_add_u64 v[4:5], v[0:1], 0, v[56:57]
	global_load_dwordx4 v[46:49], v[4:5], off
	v_or_b32_e32 v4, 8, v2
	v_ashrrev_i32_e32 v5, 31, v4
	v_or_b32_e32 v6, 12, v2
	v_lshlrev_b64 v[36:37], 12, v[4:5]
	v_ashrrev_i32_e32 v7, 31, v6
	v_lshl_add_u64 v[4:5], v[0:1], 0, v[36:37]
	v_lshlrev_b64 v[34:35], 12, v[6:7]
	v_lshl_add_u64 v[6:7], v[0:1], 0, v[34:35]
	global_load_dwordx4 v[20:23], v[4:5], off
	global_load_dwordx4 v[16:19], v[6:7], off
	v_or_b32_e32 v4, 16, v2
	v_ashrrev_i32_e32 v5, 31, v4
	v_or_b32_e32 v6, 20, v2
	v_lshl_add_u64 v[26:27], v[26:27], 0, v[38:39]
	v_mul_u32_u24_e32 v39, 0x110, v199
	v_lshlrev_b64 v[32:33], 12, v[4:5]
	v_ashrrev_i32_e32 v7, 31, v6
	v_add3_u32 v38, v44, v38, v39
	v_lshl_add_u64 v[4:5], v[0:1], 0, v[32:33]
	v_lshlrev_b64 v[30:31], 12, v[6:7]
	v_lshl_add_u64 v[6:7], v[0:1], 0, v[30:31]
	global_load_dwordx4 v[12:15], v[4:5], off
	global_load_dwordx4 v[8:11], v[6:7], off
	v_or_b32_e32 v4, 24, v2
	v_or_b32_e32 v2, 28, v2
	v_ashrrev_i32_e32 v5, 31, v4
	v_ashrrev_i32_e32 v3, 31, v2
	v_lshlrev_b64 v[28:29], 12, v[4:5]
	v_lshlrev_b64 v[24:25], 12, v[2:3]
	v_lshl_add_u64 v[4:5], v[0:1], 0, v[28:29]
	v_lshl_add_u64 v[0:1], v[0:1], 0, v[24:25]
	global_load_dwordx4 v[4:7], v[4:5], off
	s_nop 0
	global_load_dwordx4 v[0:3], v[0:1], off
	ds_read_b128 v[50:53], v38
	v_lshl_add_u64 v[36:37], v[26:27], 0, v[36:37]
	s_add_i32 s55, s55, 1
	s_mov_b64 s[24:25], 0
	s_waitcnt lgkmcnt(0)
	v_lshlrev_b32_e32 v58, 16, v50
	v_and_b32_e32 v50, 0xffff0000, v50
	s_waitcnt vmcnt(7)
	v_lshlrev_b32_e32 v39, 16, v40
	v_and_b32_e32 v40, 0xffff0000, v40
	v_mul_f32_e32 v44, 0xbfb8aa3b, v39
	v_mul_f32_e32 v45, 0xbfb8aa3b, v40
	v_exp_f32_e32 v44, v44
	v_exp_f32_e32 v45, v45
	v_add_f32_e32 v44, 1.0, v44
	v_add_f32_e32 v45, 1.0, v45
	v_rcp_f32_e32 v44, v44
	v_rcp_f32_e32 v45, v45
	v_mul_f32_e32 v39, v44, v39
	v_mul_f32_e32 v40, v45, v40
	v_mul_f32_e32 v39, v39, v58
	v_mul_f32_e32 v40, v40, v50
	v_cvt_pk_bf16_f32 v40, v39, v40
	v_lshlrev_b32_e32 v39, 16, v41
	v_and_b32_e32 v41, 0xffff0000, v41
	v_mul_f32_e32 v44, 0xbfb8aa3b, v39
	v_mul_f32_e32 v45, 0xbfb8aa3b, v41
	v_exp_f32_e32 v44, v44
	v_exp_f32_e32 v45, v45
	v_lshlrev_b32_e32 v50, 16, v51
	v_and_b32_e32 v51, 0xffff0000, v51
	v_add_f32_e32 v44, 1.0, v44
	v_add_f32_e32 v45, 1.0, v45
	v_rcp_f32_e32 v44, v44
	v_rcp_f32_e32 v45, v45
	v_mul_f32_e32 v39, v44, v39
	v_mul_f32_e32 v41, v45, v41
	v_mul_f32_e32 v39, v39, v50
	v_mul_f32_e32 v41, v41, v51
	v_cvt_pk_bf16_f32 v41, v39, v41
	v_lshlrev_b32_e32 v39, 16, v42
	v_and_b32_e32 v42, 0xffff0000, v42
	v_mul_f32_e32 v44, 0xbfb8aa3b, v39
	v_mul_f32_e32 v45, 0xbfb8aa3b, v42
	v_exp_f32_e32 v44, v44
	v_exp_f32_e32 v45, v45
	v_lshlrev_b32_e32 v50, 16, v52
	v_and_b32_e32 v51, 0xffff0000, v52
	v_add_f32_e32 v44, 1.0, v44
	v_add_f32_e32 v45, 1.0, v45
	v_rcp_f32_e32 v44, v44
	v_rcp_f32_e32 v45, v45
	v_mul_f32_e32 v39, v44, v39
	v_mul_f32_e32 v42, v45, v42
	v_mul_f32_e32 v39, v39, v50
	v_mul_f32_e32 v42, v42, v51
	v_cvt_pk_bf16_f32 v42, v39, v42
	v_lshlrev_b32_e32 v39, 16, v43
	v_and_b32_e32 v43, 0xffff0000, v43
	v_mul_f32_e32 v44, 0xbfb8aa3b, v39
	v_mul_f32_e32 v45, 0xbfb8aa3b, v43
	v_exp_f32_e32 v44, v44
	v_exp_f32_e32 v45, v45
	v_lshlrev_b32_e32 v50, 16, v53
	v_and_b32_e32 v51, 0xffff0000, v53
	v_add_f32_e32 v44, 1.0, v44
	v_add_f32_e32 v45, 1.0, v45
	v_rcp_f32_e32 v44, v44
	v_rcp_f32_e32 v45, v45
	v_mul_f32_e32 v39, v44, v39
	v_mul_f32_e32 v43, v45, v43
	v_mul_f32_e32 v39, v39, v50
	v_mul_f32_e32 v43, v43, v51
	v_lshl_add_u64 v[44:45], v[26:27], 0, v[54:55]
	v_cvt_pk_bf16_f32 v43, v39, v43
	global_store_dwordx4 v[44:45], v[40:43], off
	s_waitcnt vmcnt(7)
	v_lshlrev_b32_e32 v39, 16, v46
	v_and_b32_e32 v44, 0xffff0000, v46
	v_mul_f32_e32 v45, 0xbfb8aa3b, v39
	v_mul_f32_e32 v46, 0xbfb8aa3b, v44
	v_exp_f32_e32 v45, v45
	v_exp_f32_e32 v46, v46
	ds_read_b128 v[40:43], v38 offset:1088
	v_add_f32_e32 v45, 1.0, v45
	v_add_f32_e32 v46, 1.0, v46
	v_rcp_f32_e32 v45, v45
	v_rcp_f32_e32 v46, v46
	s_waitcnt lgkmcnt(0)
	v_lshlrev_b32_e32 v50, 16, v40
	v_and_b32_e32 v40, 0xffff0000, v40
	v_mul_f32_e32 v39, v45, v39
	v_mul_f32_e32 v44, v46, v44
	v_mul_f32_e32 v39, v39, v50
	v_mul_f32_e32 v40, v44, v40
	v_cvt_pk_bf16_f32 v40, v39, v40
	v_lshlrev_b32_e32 v39, 16, v47
	v_and_b32_e32 v44, 0xffff0000, v47
	v_mul_f32_e32 v45, 0xbfb8aa3b, v39
	v_mul_f32_e32 v46, 0xbfb8aa3b, v44
	v_exp_f32_e32 v45, v45
	v_exp_f32_e32 v46, v46
	v_lshlrev_b32_e32 v47, 16, v41
	v_and_b32_e32 v41, 0xffff0000, v41
	v_add_f32_e32 v45, 1.0, v45
	v_add_f32_e32 v46, 1.0, v46
	v_rcp_f32_e32 v45, v45
	v_rcp_f32_e32 v46, v46
	v_mul_f32_e32 v39, v45, v39
	v_mul_f32_e32 v44, v46, v44
	v_mul_f32_e32 v39, v39, v47
	v_mul_f32_e32 v41, v44, v41
	v_cvt_pk_bf16_f32 v41, v39, v41
	v_lshlrev_b32_e32 v39, 16, v48
	v_and_b32_e32 v44, 0xffff0000, v48
	v_mul_f32_e32 v45, 0xbfb8aa3b, v39
	v_mul_f32_e32 v46, 0xbfb8aa3b, v44
	v_exp_f32_e32 v45, v45
	v_exp_f32_e32 v46, v46
	v_lshlrev_b32_e32 v47, 16, v42
	v_and_b32_e32 v42, 0xffff0000, v42
	v_add_f32_e32 v45, 1.0, v45
	v_add_f32_e32 v46, 1.0, v46
	v_rcp_f32_e32 v45, v45
	v_rcp_f32_e32 v46, v46
	v_mul_f32_e32 v39, v45, v39
	v_mul_f32_e32 v44, v46, v44
	v_mul_f32_e32 v39, v39, v47
	v_mul_f32_e32 v42, v44, v42
	v_cvt_pk_bf16_f32 v42, v39, v42
	v_lshlrev_b32_e32 v39, 16, v49
	v_and_b32_e32 v44, 0xffff0000, v49
	v_mul_f32_e32 v45, 0xbfb8aa3b, v39
	v_mul_f32_e32 v46, 0xbfb8aa3b, v44
	v_exp_f32_e32 v45, v45
	v_exp_f32_e32 v46, v46
	v_lshlrev_b32_e32 v47, 16, v43
	v_and_b32_e32 v43, 0xffff0000, v43
	v_add_f32_e32 v45, 1.0, v45
	v_add_f32_e32 v46, 1.0, v46
	v_rcp_f32_e32 v45, v45
	v_rcp_f32_e32 v46, v46
	v_mul_f32_e32 v39, v45, v39
	v_mul_f32_e32 v44, v46, v44
	v_mul_f32_e32 v39, v39, v47
	v_mul_f32_e32 v43, v44, v43
	v_cvt_pk_bf16_f32 v43, v39, v43
	v_lshl_add_u64 v[44:45], v[26:27], 0, v[56:57]
	s_waitcnt vmcnt(6)
; template <int MODE> ...
;     ...
;     u32x4 gq[8];
; #pragma unroll
;     for (int i = 0; i < 8; ++i) { const int id = lane + 64 * i; gq[i] = *(const u32x4*)(Gw + (long)(g * 32 + (id >> 4)) * 2048 + kh * 128 + (id & 15) * 8); }
; #pragma unroll
;     for (int i = 0; i < 8; ++i) { const int id = lane + 64 * i, row = id >> 4, cc = id & 15;
;       const u32x4 zz = *(const u32x4*)(zt + row * 272 + cc * 16);
;       unsigned yo[4];
; #pragma unroll
;       for (int k = 0; k < 4; ++k) { const unsigned zw = zz[k], gw_ = gq[i][k];
;         const float z0 = __builtin_bit_cast(float, zw << 16), z1 = __builtin_bit_cast(float, zw & 0xffff0000u);
;         const float g0 = __builtin_bit_cast(float, gw_ << 16), g1 = __builtin_bit_cast(float, gw_ & 0xffff0000u);
;         yo[k] = cvtpk(z0 * (g0 * __builtin_amdgcn_rcpf(1.f + __expf(-g0))), z1 * (g1 * __builtin_amdgcn_rcpf(1.f + __expf(-g1)))); }
;       *(u32x4*)(A2w + (long)(g * 32 + row) * 2048 + kh * 128 + cc * 8) = (u32x4){yo[0], yo[1], yo[2], yo[3]}; }
	v_lshlrev_b32_e32 v39, 16, v20
	v_and_b32_e32 v20, 0xffff0000, v20
	global_store_dwordx4 v[44:45], v[40:43], off
	v_mul_f32_e32 v44, 0xbfb8aa3b, v39
	v_mul_f32_e32 v45, 0xbfb8aa3b, v20
	v_exp_f32_e32 v44, v44
	v_exp_f32_e32 v45, v45
	ds_read_b128 v[40:43], v38 offset:2176
	v_add_f32_e32 v44, 1.0, v44
	v_add_f32_e32 v45, 1.0, v45
	v_rcp_f32_e32 v44, v44
	v_rcp_f32_e32 v45, v45
	s_waitcnt lgkmcnt(0)
	v_lshlrev_b32_e32 v46, 16, v40
	v_and_b32_e32 v40, 0xffff0000, v40
	v_mul_f32_e32 v39, v44, v39
	v_mul_f32_e32 v20, v45, v20
	v_mul_f32_e32 v39, v39, v46
	v_mul_f32_e32 v20, v20, v40
	v_cvt_pk_bf16_f32 v20, v39, v20
	v_lshlrev_b32_e32 v39, 16, v21
	v_and_b32_e32 v21, 0xffff0000, v21
	v_mul_f32_e32 v40, 0xbfb8aa3b, v39
	v_mul_f32_e32 v44, 0xbfb8aa3b, v21
	v_exp_f32_e32 v40, v40
	v_exp_f32_e32 v44, v44
	v_lshlrev_b32_e32 v45, 16, v41
	v_and_b32_e32 v41, 0xffff0000, v41
	v_add_f32_e32 v40, 1.0, v40
	v_add_f32_e32 v44, 1.0, v44
	v_rcp_f32_e32 v40, v40
	v_rcp_f32_e32 v44, v44
	v_mul_f32_e32 v39, v40, v39
	v_mul_f32_e32 v21, v44, v21
	v_mul_f32_e32 v39, v39, v45
	v_mul_f32_e32 v21, v21, v41
	v_cvt_pk_bf16_f32 v21, v39, v21
	v_lshlrev_b32_e32 v39, 16, v22
	v_and_b32_e32 v22, 0xffff0000, v22
	v_mul_f32_e32 v40, 0xbfb8aa3b, v39
	v_mul_f32_e32 v41, 0xbfb8aa3b, v22
	v_exp_f32_e32 v40, v40
	v_exp_f32_e32 v41, v41
	v_lshlrev_b32_e32 v44, 16, v42
	v_and_b32_e32 v42, 0xffff0000, v42
	v_add_f32_e32 v40, 1.0, v40
	v_add_f32_e32 v41, 1.0, v41
	v_rcp_f32_e32 v40, v40
	v_rcp_f32_e32 v41, v41
	v_mul_f32_e32 v39, v40, v39
	v_mul_f32_e32 v22, v41, v22
	v_mul_f32_e32 v39, v39, v44
	v_mul_f32_e32 v22, v22, v42
	v_cvt_pk_bf16_f32 v22, v39, v22
	v_lshlrev_b32_e32 v39, 16, v23
	v_and_b32_e32 v23, 0xffff0000, v23
	v_mul_f32_e32 v41, 0xbfb8aa3b, v23
	v_mul_f32_e32 v40, 0xbfb8aa3b, v39
	v_exp_f32_e32 v41, v41
	v_exp_f32_e32 v40, v40
	v_lshlrev_b32_e32 v42, 16, v43
	v_and_b32_e32 v43, 0xffff0000, v43
	v_add_f32_e32 v41, 1.0, v41
	v_add_f32_e32 v40, 1.0, v40
	v_rcp_f32_e32 v41, v41
	v_rcp_f32_e32 v40, v40
	v_mul_f32_e32 v23, v41, v23
	v_mul_f32_e32 v39, v40, v39
	v_mul_f32_e32 v23, v23, v43
	v_mul_f32_e32 v39, v39, v42
	v_cvt_pk_bf16_f32 v23, v39, v23
	global_store_dwordx4 v[36:37], v[20:23], off
	s_waitcnt vmcnt(7)
	v_lshlrev_b32_e32 v36, 16, v16
	v_and_b32_e32 v16, 0xffff0000, v16
	v_mul_f32_e32 v37, 0xbfb8aa3b, v36
	v_mul_f32_e32 v39, 0xbfb8aa3b, v16
	v_exp_f32_e32 v37, v37
	v_exp_f32_e32 v39, v39
	ds_read_b128 v[20:23], v38 offset:3264
	v_add_f32_e32 v37, 1.0, v37
	v_add_f32_e32 v39, 1.0, v39
	v_rcp_f32_e32 v37, v37
	v_rcp_f32_e32 v39, v39
	s_waitcnt lgkmcnt(0)
	v_lshlrev_b32_e32 v40, 16, v20
	v_and_b32_e32 v20, 0xffff0000, v20
	v_mul_f32_e32 v36, v37, v36
	v_mul_f32_e32 v16, v39, v16
	v_mul_f32_e32 v36, v36, v40
	v_mul_f32_e32 v16, v16, v20
	v_lshlrev_b32_e32 v20, 16, v17
	v_and_b32_e32 v17, 0xffff0000, v17
	v_cvt_pk_bf16_f32 v16, v36, v16
	v_mul_f32_e32 v36, 0xbfb8aa3b, v20
	v_mul_f32_e32 v37, 0xbfb8aa3b, v17
	v_exp_f32_e32 v36, v36
	v_exp_f32_e32 v37, v37
	v_lshlrev_b32_e32 v39, 16, v21
	v_and_b32_e32 v21, 0xffff0000, v21
	v_add_f32_e32 v36, 1.0, v36
	v_add_f32_e32 v37, 1.0, v37
	v_rcp_f32_e32 v36, v36
	v_rcp_f32_e32 v37, v37
	v_mul_f32_e32 v20, v36, v20
	v_mul_f32_e32 v17, v37, v17
	v_mul_f32_e32 v20, v20, v39
	v_mul_f32_e32 v17, v17, v21
	v_cvt_pk_bf16_f32 v17, v20, v17
	v_lshlrev_b32_e32 v20, 16, v18
	v_and_b32_e32 v18, 0xffff0000, v18
	v_mul_f32_e32 v21, 0xbfb8aa3b, v20
	v_mul_f32_e32 v36, 0xbfb8aa3b, v18
	v_exp_f32_e32 v21, v21
	v_exp_f32_e32 v36, v36
	v_lshlrev_b32_e32 v37, 16, v22
	v_and_b32_e32 v22, 0xffff0000, v22
	v_add_f32_e32 v21, 1.0, v21
	v_add_f32_e32 v36, 1.0, v36
	v_rcp_f32_e32 v21, v21
	v_rcp_f32_e32 v36, v36
	v_mul_f32_e32 v20, v21, v20
	v_mul_f32_e32 v18, v36, v18
	v_mul_f32_e32 v20, v20, v37
	v_mul_f32_e32 v18, v18, v22
	v_cvt_pk_bf16_f32 v18, v20, v18
	v_lshlrev_b32_e32 v20, 16, v19
	v_and_b32_e32 v19, 0xffff0000, v19
	v_mul_f32_e32 v21, 0xbfb8aa3b, v20
	v_mul_f32_e32 v22, 0xbfb8aa3b, v19
	v_exp_f32_e32 v21, v21
	v_exp_f32_e32 v22, v22
	v_lshlrev_b32_e32 v36, 16, v23
	v_and_b32_e32 v23, 0xffff0000, v23
	v_add_f32_e32 v21, 1.0, v21
	v_add_f32_e32 v22, 1.0, v22
	v_rcp_f32_e32 v21, v21
	v_rcp_f32_e32 v22, v22
	v_mul_f32_e32 v20, v21, v20
	v_mul_f32_e32 v19, v22, v19
	v_mul_f32_e32 v20, v20, v36
	v_mul_f32_e32 v19, v19, v23
	v_cvt_pk_bf16_f32 v19, v20, v19
	v_lshl_add_u64 v[20:21], v[26:27], 0, v[34:35]
	global_store_dwordx4 v[20:21], v[16:19], off
	s_waitcnt vmcnt(7)
	v_lshlrev_b32_e32 v20, 16, v12
	v_and_b32_e32 v12, 0xffff0000, v12
	v_mul_f32_e32 v21, 0xbfb8aa3b, v20
	v_mul_f32_e32 v22, 0xbfb8aa3b, v12
	v_exp_f32_e32 v21, v21
	v_exp_f32_e32 v22, v22
	ds_read_b128 v[16:19], v38 offset:4352
	v_add_f32_e32 v21, 1.0, v21
	v_add_f32_e32 v22, 1.0, v22
	v_rcp_f32_e32 v21, v21
	v_rcp_f32_e32 v22, v22
	s_waitcnt lgkmcnt(0)
; template <int MODE> ...
;     ...
;     u32x4 gq[8];
; #pragma unroll
;     for (int i = 0; i < 8; ++i) { const int id = lane + 64 * i; gq[i] = *(const u32x4*)(Gw + (long)(g * 32 + (id >> 4)) * 2048 + kh * 128 + (id & 15) * 8); }
; #pragma unroll
;     for (int i = 0; i < 8; ++i) { const int id = lane + 64 * i, row = id >> 4, cc = id & 15;
;       const u32x4 zz = *(const u32x4*)(zt + row * 272 + cc * 16);
;       unsigned yo[4];
; #pragma unroll
;       for (int k = 0; k < 4; ++k) { const unsigned zw = zz[k], gw_ = gq[i][k];
;         const float z0 = __builtin_bit_cast(float, zw << 16), z1 = __builtin_bit_cast(float, zw & 0xffff0000u);
;         const float g0 = __builtin_bit_cast(float, gw_ << 16), g1 = __builtin_bit_cast(float, gw_ & 0xffff0000u);
;         yo[k] = cvtpk(z0 * (g0 * __builtin_amdgcn_rcpf(1.f + __expf(-g0))), z1 * (g1 * __builtin_amdgcn_rcpf(1.f + __expf(-g1)))); }
;       *(u32x4*)(A2w + (long)(g * 32 + row) * 2048 + kh * 128 + cc * 8) = (u32x4){yo[0], yo[1], yo[2], yo[3]}; }
	v_lshlrev_b32_e32 v23, 16, v16
	v_and_b32_e32 v16, 0xffff0000, v16
	v_mul_f32_e32 v20, v21, v20
	v_mul_f32_e32 v12, v22, v12
	v_mul_f32_e32 v20, v20, v23
	v_mul_f32_e32 v12, v12, v16
	v_lshlrev_b32_e32 v16, 16, v13
	v_and_b32_e32 v13, 0xffff0000, v13
	v_cvt_pk_bf16_f32 v12, v20, v12
	v_mul_f32_e32 v20, 0xbfb8aa3b, v16
	v_mul_f32_e32 v21, 0xbfb8aa3b, v13
	v_exp_f32_e32 v20, v20
	v_exp_f32_e32 v21, v21
	v_lshlrev_b32_e32 v22, 16, v17
	v_and_b32_e32 v17, 0xffff0000, v17
	v_add_f32_e32 v20, 1.0, v20
	v_add_f32_e32 v21, 1.0, v21
	v_rcp_f32_e32 v20, v20
	v_rcp_f32_e32 v21, v21
	v_mul_f32_e32 v16, v20, v16
	v_mul_f32_e32 v13, v21, v13
	v_mul_f32_e32 v16, v16, v22
	v_mul_f32_e32 v13, v13, v17
	v_cvt_pk_bf16_f32 v13, v16, v13
	v_lshlrev_b32_e32 v16, 16, v14
	v_and_b32_e32 v14, 0xffff0000, v14
	v_mul_f32_e32 v17, 0xbfb8aa3b, v16
	v_mul_f32_e32 v20, 0xbfb8aa3b, v14
	v_exp_f32_e32 v17, v17
	v_exp_f32_e32 v20, v20
	v_lshlrev_b32_e32 v21, 16, v18
	v_and_b32_e32 v18, 0xffff0000, v18
	v_add_f32_e32 v17, 1.0, v17
	v_add_f32_e32 v20, 1.0, v20
	v_rcp_f32_e32 v17, v17
	v_rcp_f32_e32 v20, v20
	v_mul_f32_e32 v16, v17, v16
	v_mul_f32_e32 v14, v20, v14
	v_mul_f32_e32 v16, v16, v21
	v_mul_f32_e32 v14, v14, v18
	v_cvt_pk_bf16_f32 v14, v16, v14
	v_lshlrev_b32_e32 v16, 16, v15
	v_and_b32_e32 v15, 0xffff0000, v15
	v_mul_f32_e32 v17, 0xbfb8aa3b, v16
	v_mul_f32_e32 v18, 0xbfb8aa3b, v15
	v_exp_f32_e32 v17, v17
	v_exp_f32_e32 v18, v18
	v_lshlrev_b32_e32 v20, 16, v19
	v_and_b32_e32 v19, 0xffff0000, v19
	v_add_f32_e32 v17, 1.0, v17
	v_add_f32_e32 v18, 1.0, v18
	v_rcp_f32_e32 v17, v17
	v_rcp_f32_e32 v18, v18
	v_mul_f32_e32 v16, v17, v16
	v_mul_f32_e32 v15, v18, v15
	v_mul_f32_e32 v16, v16, v20
	v_mul_f32_e32 v15, v15, v19
	v_cvt_pk_bf16_f32 v15, v16, v15
	v_lshl_add_u64 v[16:17], v[26:27], 0, v[32:33]
	global_store_dwordx4 v[16:17], v[12:15], off
	s_waitcnt vmcnt(7)
	v_lshlrev_b32_e32 v16, 16, v8
	v_and_b32_e32 v8, 0xffff0000, v8
	v_mul_f32_e32 v17, 0xbfb8aa3b, v16
	v_mul_f32_e32 v18, 0xbfb8aa3b, v8
	v_exp_f32_e32 v17, v17
	v_exp_f32_e32 v18, v18
	ds_read_b128 v[12:15], v38 offset:5440
	v_add_f32_e32 v17, 1.0, v17
	v_add_f32_e32 v18, 1.0, v18
	v_rcp_f32_e32 v17, v17
	v_rcp_f32_e32 v18, v18
	s_waitcnt lgkmcnt(0)
	v_lshlrev_b32_e32 v19, 16, v12
	v_and_b32_e32 v12, 0xffff0000, v12
	v_mul_f32_e32 v16, v17, v16
	v_mul_f32_e32 v8, v18, v8
	v_mul_f32_e32 v16, v16, v19
	v_mul_f32_e32 v8, v8, v12
	v_lshlrev_b32_e32 v12, 16, v9
	v_and_b32_e32 v9, 0xffff0000, v9
	v_cvt_pk_bf16_f32 v8, v16, v8
	v_mul_f32_e32 v16, 0xbfb8aa3b, v12
	v_mul_f32_e32 v17, 0xbfb8aa3b, v9
	v_exp_f32_e32 v16, v16
	v_exp_f32_e32 v17, v17
	v_lshlrev_b32_e32 v18, 16, v13
	v_and_b32_e32 v13, 0xffff0000, v13
	v_add_f32_e32 v16, 1.0, v16
	v_add_f32_e32 v17, 1.0, v17
	v_rcp_f32_e32 v16, v16
	v_rcp_f32_e32 v17, v17
	v_mul_f32_e32 v12, v16, v12
	v_mul_f32_e32 v9, v17, v9
	v_mul_f32_e32 v12, v12, v18
	v_mul_f32_e32 v9, v9, v13
	v_cvt_pk_bf16_f32 v9, v12, v9
	v_lshlrev_b32_e32 v12, 16, v10
	v_and_b32_e32 v10, 0xffff0000, v10
	v_mul_f32_e32 v13, 0xbfb8aa3b, v12
	v_mul_f32_e32 v16, 0xbfb8aa3b, v10
	v_exp_f32_e32 v13, v13
	v_exp_f32_e32 v16, v16
	v_lshlrev_b32_e32 v17, 16, v14
	v_and_b32_e32 v14, 0xffff0000, v14
	v_add_f32_e32 v13, 1.0, v13
	v_add_f32_e32 v16, 1.0, v16
	v_rcp_f32_e32 v13, v13
	v_rcp_f32_e32 v16, v16
	v_mul_f32_e32 v12, v13, v12
	v_mul_f32_e32 v10, v16, v10
	v_mul_f32_e32 v12, v12, v17
	v_mul_f32_e32 v10, v10, v14
	v_cvt_pk_bf16_f32 v10, v12, v10
	v_lshlrev_b32_e32 v12, 16, v11
	v_and_b32_e32 v11, 0xffff0000, v11
	v_mul_f32_e32 v13, 0xbfb8aa3b, v12
	v_mul_f32_e32 v14, 0xbfb8aa3b, v11
	v_exp_f32_e32 v13, v13
	v_exp_f32_e32 v14, v14
	v_lshlrev_b32_e32 v16, 16, v15
	v_and_b32_e32 v15, 0xffff0000, v15
	v_add_f32_e32 v13, 1.0, v13
	v_add_f32_e32 v14, 1.0, v14
	v_rcp_f32_e32 v13, v13
	v_rcp_f32_e32 v14, v14
	v_mul_f32_e32 v12, v13, v12
	v_mul_f32_e32 v11, v14, v11
	v_mul_f32_e32 v12, v12, v16
	v_mul_f32_e32 v11, v11, v15
	v_cvt_pk_bf16_f32 v11, v12, v11
	v_lshl_add_u64 v[12:13], v[26:27], 0, v[30:31]
	global_store_dwordx4 v[12:13], v[8:11], off
	s_waitcnt vmcnt(7)
; template <int MODE> ...
;     ...
;     for (int i = 0; i < 8; ++i) { const int id = lane + 64 * i; gq[i] = *(const u32x4*)(Gw + (long)(g * 32 + (id >> 4)) * 2048 + kh * 128 + (id & 15) * 8); }
; #pragma unroll
;     for (int i = 0; i < 8; ++i) { const int id = lane + 64 * i, row = id >> 4, cc = id & 15;
;       const u32x4 zz = *(const u32x4*)(zt + row * 272 + cc * 16);
;       unsigned yo[4];
; #pragma unroll
;       for (int k = 0; k < 4; ++k) { const unsigned zw = zz[k], gw_ = gq[i][k];
;         const float z0 = __builtin_bit_cast(float, zw << 16), z1 = __builtin_bit_cast(float, zw & 0xffff0000u);
;         const float g0 = __builtin_bit_cast(float, gw_ << 16), g1 = __builtin_bit_cast(float, gw_ & 0xffff0000u);
;         yo[k] = cvtpk(z0 * (g0 * __builtin_amdgcn_rcpf(1.f + __expf(-g0))), z1 * (g1 * __builtin_amdgcn_rcpf(1.f + __expf(-g1)))); }
;       *(u32x4*)(A2w + (long)(g * 32 + row) * 2048 + kh * 128 + cc * 8) = (u32x4){yo[0], yo[1], yo[2], yo[3]}; }
;     asm volatile("s_waitcnt vmcnt(0)" ::: "memory"); __syncthreads();
	v_lshlrev_b32_e32 v12, 16, v4
	v_and_b32_e32 v4, 0xffff0000, v4
	v_mul_f32_e32 v13, 0xbfb8aa3b, v12
	v_mul_f32_e32 v14, 0xbfb8aa3b, v4
	v_exp_f32_e32 v13, v13
	v_exp_f32_e32 v14, v14
	ds_read_b128 v[8:11], v38 offset:6528
	v_add_f32_e32 v13, 1.0, v13
	v_add_f32_e32 v14, 1.0, v14
	v_rcp_f32_e32 v13, v13
	v_rcp_f32_e32 v14, v14
	s_waitcnt lgkmcnt(0)
	v_lshlrev_b32_e32 v15, 16, v8
	v_and_b32_e32 v8, 0xffff0000, v8
	v_mul_f32_e32 v12, v13, v12
	v_mul_f32_e32 v4, v14, v4
	v_mul_f32_e32 v12, v12, v15
	v_mul_f32_e32 v4, v4, v8
	v_lshlrev_b32_e32 v8, 16, v5
	v_and_b32_e32 v5, 0xffff0000, v5
	v_cvt_pk_bf16_f32 v4, v12, v4
	v_mul_f32_e32 v12, 0xbfb8aa3b, v8
	v_mul_f32_e32 v13, 0xbfb8aa3b, v5
	v_exp_f32_e32 v12, v12
	v_exp_f32_e32 v13, v13
	v_lshlrev_b32_e32 v14, 16, v9
	v_and_b32_e32 v9, 0xffff0000, v9
	v_add_f32_e32 v12, 1.0, v12
	v_add_f32_e32 v13, 1.0, v13
	v_rcp_f32_e32 v12, v12
	v_rcp_f32_e32 v13, v13
	v_mul_f32_e32 v8, v12, v8
	v_mul_f32_e32 v5, v13, v5
	v_mul_f32_e32 v8, v8, v14
	v_mul_f32_e32 v5, v5, v9
	v_cvt_pk_bf16_f32 v5, v8, v5
	v_lshlrev_b32_e32 v8, 16, v6
	v_and_b32_e32 v6, 0xffff0000, v6
	v_mul_f32_e32 v9, 0xbfb8aa3b, v8
	v_mul_f32_e32 v12, 0xbfb8aa3b, v6
	v_exp_f32_e32 v9, v9
	v_exp_f32_e32 v12, v12
	v_lshlrev_b32_e32 v13, 16, v10
	v_and_b32_e32 v10, 0xffff0000, v10
	v_add_f32_e32 v9, 1.0, v9
	v_add_f32_e32 v12, 1.0, v12
	v_rcp_f32_e32 v9, v9
	v_rcp_f32_e32 v12, v12
	v_mul_f32_e32 v8, v9, v8
	v_mul_f32_e32 v6, v12, v6
	v_mul_f32_e32 v8, v8, v13
	v_mul_f32_e32 v6, v6, v10
	v_cvt_pk_bf16_f32 v6, v8, v6
	v_lshlrev_b32_e32 v8, 16, v7
	v_and_b32_e32 v7, 0xffff0000, v7
	v_mul_f32_e32 v9, 0xbfb8aa3b, v8
	v_mul_f32_e32 v10, 0xbfb8aa3b, v7
	v_exp_f32_e32 v9, v9
	v_exp_f32_e32 v10, v10
	v_lshlrev_b32_e32 v12, 16, v11
	v_and_b32_e32 v11, 0xffff0000, v11
	v_add_f32_e32 v9, 1.0, v9
	v_add_f32_e32 v10, 1.0, v10
	v_rcp_f32_e32 v9, v9
	v_rcp_f32_e32 v10, v10
	v_mul_f32_e32 v8, v9, v8
	v_mul_f32_e32 v7, v10, v7
	v_mul_f32_e32 v8, v8, v12
	v_mul_f32_e32 v7, v7, v11
	v_cvt_pk_bf16_f32 v7, v8, v7
	v_lshl_add_u64 v[8:9], v[26:27], 0, v[28:29]
	global_store_dwordx4 v[8:9], v[4:7], off
	s_waitcnt vmcnt(7)
	v_lshlrev_b32_e32 v8, 16, v0
	v_and_b32_e32 v0, 0xffff0000, v0
	v_mul_f32_e32 v9, 0xbfb8aa3b, v8
	v_mul_f32_e32 v10, 0xbfb8aa3b, v0
	v_exp_f32_e32 v9, v9
	v_exp_f32_e32 v10, v10
	ds_read_b128 v[4:7], v38 offset:7616
	v_add_f32_e32 v9, 1.0, v9
	v_add_f32_e32 v10, 1.0, v10
	v_rcp_f32_e32 v9, v9
	v_rcp_f32_e32 v10, v10
	s_waitcnt lgkmcnt(0)
	v_lshlrev_b32_e32 v11, 16, v4
	v_and_b32_e32 v4, 0xffff0000, v4
	v_mul_f32_e32 v8, v9, v8
	v_mul_f32_e32 v0, v10, v0
	v_mul_f32_e32 v8, v8, v11
	v_mul_f32_e32 v0, v0, v4
	v_lshlrev_b32_e32 v4, 16, v1
	v_and_b32_e32 v1, 0xffff0000, v1
	v_cvt_pk_bf16_f32 v0, v8, v0
	v_mul_f32_e32 v8, 0xbfb8aa3b, v4
	v_mul_f32_e32 v9, 0xbfb8aa3b, v1
	v_exp_f32_e32 v8, v8
	v_exp_f32_e32 v9, v9
	v_lshlrev_b32_e32 v10, 16, v5
	v_and_b32_e32 v5, 0xffff0000, v5
	v_add_f32_e32 v8, 1.0, v8
	v_add_f32_e32 v9, 1.0, v9
	v_rcp_f32_e32 v8, v8
	v_rcp_f32_e32 v9, v9
	v_mul_f32_e32 v4, v8, v4
	v_mul_f32_e32 v1, v9, v1
	v_mul_f32_e32 v4, v4, v10
	v_mul_f32_e32 v1, v1, v5
	v_cvt_pk_bf16_f32 v1, v4, v1
	v_lshlrev_b32_e32 v4, 16, v2
	v_and_b32_e32 v2, 0xffff0000, v2
	v_mul_f32_e32 v5, 0xbfb8aa3b, v4
	v_mul_f32_e32 v8, 0xbfb8aa3b, v2
	v_exp_f32_e32 v5, v5
	v_exp_f32_e32 v8, v8
	v_lshlrev_b32_e32 v9, 16, v6
	v_and_b32_e32 v6, 0xffff0000, v6
	v_add_f32_e32 v5, 1.0, v5
	v_add_f32_e32 v8, 1.0, v8
	v_rcp_f32_e32 v5, v5
	v_rcp_f32_e32 v8, v8
	v_mul_f32_e32 v4, v5, v4
	v_mul_f32_e32 v2, v8, v2
	v_mul_f32_e32 v4, v4, v9
	v_mul_f32_e32 v2, v2, v6
	v_cvt_pk_bf16_f32 v2, v4, v2
	v_lshlrev_b32_e32 v4, 16, v3
	v_and_b32_e32 v3, 0xffff0000, v3
	v_mul_f32_e32 v5, 0xbfb8aa3b, v4
	v_mul_f32_e32 v6, 0xbfb8aa3b, v3
	v_exp_f32_e32 v5, v5
	v_exp_f32_e32 v6, v6
	v_lshlrev_b32_e32 v8, 16, v7
	v_and_b32_e32 v7, 0xffff0000, v7
	v_add_f32_e32 v5, 1.0, v5
	v_add_f32_e32 v6, 1.0, v6
	v_rcp_f32_e32 v5, v5
	v_rcp_f32_e32 v6, v6
	v_mul_f32_e32 v4, v5, v4
	v_mul_f32_e32 v3, v6, v3
	v_mul_f32_e32 v4, v4, v8
	v_mul_f32_e32 v3, v3, v7
	v_cvt_pk_bf16_f32 v3, v4, v3
	v_lshl_add_u64 v[4:5], v[26:27], 0, v[24:25]
	global_store_dwordx4 v[4:5], v[0:3], off
	s_nop 1
	s_barrier

; __device__ __forceinline__ int crow(int r, int hi) { return (r & 3) + 8 * (r >> 2) + 4 * hi; }
; #define XS_WRITE(OV, BASE) do { float* xs_ = (float*)(lds + (BASE)) + ((g * 4) * 64 + lane) * 16; \
;     _Pragma("unroll") for (int d0 = 0; d0 < 4; ++d0) { float* xp = xs_ + d0 * 64 * 16; \
;       _Pragma("unroll") for (int q4 = 0; q4 < 4; ++q4) *(f32x4v*)(xp + 4 * q4) = (f32x4v){OV[d0][4 * q4], OV[d0][4 * q4 + 1], OV[d0][4 * q4 + 2], OV[d0][4 * q4 + 3]}; } } while (0)
; #define XS_WRITE(OV, BASE) do { float* xs_ = (float*)(lds + (BASE)) + ((g * 4) * 64 + lane) * 16; \
;     _Pragma("unroll") for (int d0 = 0; d0 < 4; ++d0) { float* xp = xs_ + d0 * 64 * 16; \
;       _Pragma("unroll") for (int q4 = 0; q4 < 4; ++q4) *(f32x4v*)(xp + 4 * q4) = (f32x4v){OV[d0][4 * q4], OV[d0][4 * q4 + 1], OV[d0][4 * q4 + 2], OV[d0][4 * q4 + 3]}; } } while (0)
; template <int MODE> ...
;     ...
;   f32x16* olo = o; f32x16* ohi = o + 4;
;   if (kh) { XS_WRITE(olo, 0); } else { XS_WRITE(ohi, 65536); }
;   __syncthreads();
;   if (kh) { XS_ADD(ohi, 65536);
; #pragma unroll
;     for (int d0 = 0; d0 < 4; ++d0) o[d0] = o[4 + d0]; }
;   else { XS_ADD(olo, 0); }
;     ...
;   float rli[16];
; #pragma unroll
;   for (int r = 0; r < 16; ++r) { const int row = crow(r, hi); const float* lp = L_lds + (g * 4) * 32 + row; rli[r] = __builtin_amdgcn_rcpf((lp[0] + lp[32]) + (lp[64] + lp[96])); }
;   float* Ow = Ob + (long)(g * 32) * LDO + kh * 128;
.LBB0_1022:
	s_or_b64 exec, exec, s[24:25]
	v_add3_u32 v80, v129, v128, v130
	ds_read_b128 v[64:67], v80
	ds_read_b128 v[68:71], v80 offset:16
	ds_read_b128 v[72:75], v80 offset:32
	ds_read_b128 v[76:79], v80 offset:48
	s_ashr_i32 s24, s40, 3
	s_ashr_i32 s25, s24, 31
	s_waitcnt lgkmcnt(2)
	v_add_f32_e32 v68, v52, v68
	v_add_f32_e32 v64, v48, v64
	v_add_f32_e32 v65, v49, v65
	v_add_f32_e32 v66, v50, v66
	v_add_f32_e32 v67, v51, v67
	ds_read_b128 v[48:51], v80 offset:4096
	v_add_f32_e32 v69, v53, v69
	v_add_f32_e32 v70, v54, v70
	v_add_f32_e32 v71, v55, v71
	ds_read_b128 v[52:55], v80 offset:4112
	s_waitcnt lgkmcnt(1)
	v_add_f32_e32 v48, v32, v48
	v_add_f32_e32 v49, v33, v49
	v_add_f32_e32 v50, v34, v50
	v_add_f32_e32 v51, v35, v51
	ds_read_b128 v[32:35], v80 offset:4128
	s_waitcnt lgkmcnt(1)
	v_add_f32_e32 v52, v36, v52
	v_add_f32_e32 v53, v37, v53
	v_add_f32_e32 v54, v38, v54
	v_add_f32_e32 v55, v39, v55
	ds_read_b128 v[36:39], v80 offset:4144
	s_waitcnt lgkmcnt(1)
	v_add_f32_e32 v40, v40, v32
	v_add_f32_e32 v41, v41, v33
	v_add_f32_e32 v42, v42, v34
	v_add_f32_e32 v43, v43, v35
	ds_read_b128 v[32:35], v80 offset:8192
	s_waitcnt lgkmcnt(1)
	v_add_f32_e32 v44, v44, v36
	v_add_f32_e32 v45, v45, v37
	v_add_f32_e32 v46, v46, v38
	v_add_f32_e32 v47, v47, v39
	ds_read_b128 v[36:39], v80 offset:8208
	s_waitcnt lgkmcnt(1)
	v_add_f32_e32 v32, v16, v32
	v_add_f32_e32 v33, v17, v33
	v_add_f32_e32 v34, v18, v34
	v_add_f32_e32 v35, v19, v35
	ds_read_b128 v[16:19], v80 offset:8224
	s_waitcnt lgkmcnt(1)
	v_add_f32_e32 v36, v20, v36
	v_add_f32_e32 v37, v21, v37
	v_add_f32_e32 v38, v22, v38
	v_add_f32_e32 v39, v23, v39
	ds_read_b128 v[20:23], v80 offset:8240
	v_add_f32_e32 v56, v56, v72
	v_add_f32_e32 v57, v57, v73
	v_add_f32_e32 v58, v58, v74
	v_add_f32_e32 v59, v59, v75
	s_waitcnt lgkmcnt(1)
	v_add_f32_e32 v72, v24, v16
	v_add_f32_e32 v73, v25, v17
	v_add_f32_e32 v74, v26, v18
	v_add_f32_e32 v75, v27, v19
	ds_read_b128 v[16:19], v80 offset:12288
	v_add_f32_e32 v60, v60, v76
	v_add_f32_e32 v61, v61, v77
	v_add_f32_e32 v62, v62, v78
	v_add_f32_e32 v63, v63, v79
	s_waitcnt lgkmcnt(1)
	v_add_f32_e32 v76, v28, v20
	v_add_f32_e32 v77, v29, v21
	v_add_f32_e32 v78, v30, v22
	v_add_f32_e32 v79, v31, v23
	ds_read_b128 v[20:23], v80 offset:12304
	s_lshl_b32 s2, s40, 8
	s_and_b32 s94, s2, 0x700
	s_lshl_b64 s[2:3], s[24:25], 27
	s_lshl_b64 s[28:29], s[28:29], 20
	s_waitcnt lgkmcnt(1)
	v_add_f32_e32 v81, v0, v16
	v_add_f32_e32 v82, v1, v17
	v_add_f32_e32 v83, v2, v18
	v_add_f32_e32 v84, v3, v19
	ds_read_b128 v[0:3], v80 offset:12320
	s_add_u32 s2, s38, s2
	s_addc_u32 s3, s39, s3
	s_add_u32 s2, s2, s28
	s_waitcnt lgkmcnt(1)
	v_add_f32_e32 v85, v4, v20
	v_add_f32_e32 v86, v5, v21
	v_add_f32_e32 v87, v6, v22
	v_add_f32_e32 v88, v7, v23
	ds_read_b128 v[4:7], v80 offset:12336
	s_addc_u32 s3, s3, s29
	s_lshl_b32 s25, s94, 2
	s_add_u32 s28, s2, s25
	s_waitcnt lgkmcnt(1)
	v_add_f32_e32 v80, v8, v0
	v_and_b32_e32 v0, 0x3fffff80, v197
	s_addc_u32 s29, s3, 0
	v_lshlrev_b32_e32 v0, 2, v0
	s_add_i32 s25, 0, 0x20000
	v_add3_u32 v96, s25, v0, v194
	v_add_f32_e32 v89, v9, v1
	v_add_f32_e32 v90, v10, v2
	v_add_f32_e32 v91, v11, v3
	s_waitcnt lgkmcnt(0)
	v_add_f32_e32 v92, v12, v4
	v_add_f32_e32 v93, v13, v5
	v_add_f32_e32 v94, v14, v6
	v_add_f32_e32 v95, v15, v7
	ds_read_b128 v[0:3], v96 offset:128
	ds_read_b128 v[4:7], v96
	ds_read_b128 v[8:11], v96 offset:32
	ds_read_b128 v[12:15], v96 offset:256
	ds_read_b128 v[16:19], v96 offset:384
	ds_read_b128 v[20:23], v96 offset:160
	s_waitcnt lgkmcnt(4)
	v_add_f32_e32 v0, v4, v0
	ds_read_b128 v[24:27], v96 offset:288
	ds_read_b128 v[28:31], v96 offset:416
	v_ashrrev_i32_e32 v197, 31, v196
	s_waitcnt lgkmcnt(3)
	v_add_f32_e32 v4, v12, v16
	v_add_f32_e32 v0, v0, v4
	v_rcp_f32_e32 v97, v0
	v_add_f32_e32 v0, v5, v1
	v_add_f32_e32 v1, v13, v17
	v_add_f32_e32 v0, v0, v1
	v_rcp_f32_e32 v98, v0
	v_add_f32_e32 v0, v6, v2
	v_add_f32_e32 v1, v14, v18
	v_add_f32_e32 v0, v0, v1
	v_rcp_f32_e32 v99, v0
	v_add_f32_e32 v0, v7, v3
	v_add_f32_e32 v1, v15, v19
	v_add_f32_e32 v0, v0, v1
	v_rcp_f32_e32 v100, v0
	s_waitcnt lgkmcnt(2)
	v_add_f32_e32 v0, v8, v20
	s_waitcnt lgkmcnt(0)
	v_add_f32_e32 v1, v24, v28
	v_add_f32_e32 v0, v0, v1
	v_rcp_f32_e32 v101, v0
	v_add_f32_e32 v0, v9, v21
	v_add_f32_e32 v1, v25, v29
	v_add_f32_e32 v0, v0, v1
	v_rcp_f32_e32 v102, v0
	v_add_f32_e32 v0, v10, v22
	v_add_f32_e32 v1, v26, v30
	v_add_f32_e32 v0, v0, v1
	v_rcp_f32_e32 v103, v0
	v_add_f32_e32 v0, v11, v23
	v_add_f32_e32 v1, v27, v31
	v_add_f32_e32 v0, v0, v1
	v_rcp_f32_e32 v104, v0
	ds_read_b128 v[0:3], v96 offset:64
	ds_read_b128 v[4:7], v96 offset:192
	ds_read_b128 v[8:11], v96 offset:320
	ds_read_b128 v[12:15], v96 offset:448
	ds_read_b128 v[16:19], v96 offset:96
	ds_read_b128 v[20:23], v96 offset:224
	s_waitcnt lgkmcnt(4)
	v_add_f32_e32 v0, v0, v4
	ds_read_b128 v[24:27], v96 offset:352
	ds_read_b128 v[28:31], v96 offset:480
	s_waitcnt lgkmcnt(4)
	v_add_f32_e32 v4, v8, v12
	v_add_f32_e32 v0, v0, v4
	v_rcp_f32_e32 v4, v0
	v_add_f32_e32 v0, v1, v5
	v_add_f32_e32 v1, v9, v13
	v_add_f32_e32 v0, v0, v1
	v_rcp_f32_e32 v5, v0
	v_add_f32_e32 v0, v2, v6
	v_add_f32_e32 v1, v10, v14
	v_add_f32_e32 v0, v0, v1
	v_rcp_f32_e32 v6, v0
	v_add_f32_e32 v0, v3, v7
	v_add_f32_e32 v1, v11, v15
	v_add_f32_e32 v0, v0, v1
	v_rcp_f32_e32 v7, v0
	s_waitcnt lgkmcnt(2)
	v_add_f32_e32 v0, v16, v20
	s_waitcnt lgkmcnt(0)
; __device__ __forceinline__ int crow(int r, int hi) { return (r & 3) + 8 * (r >> 2) + 4 * hi; }
; template <int MODE> ...
;     ...
;   float rli[16];
; #pragma unroll
;   for (int r = 0; r < 16; ++r) { const int row = crow(r, hi); const float* lp = L_lds + (g * 4) * 32 + row; rli[r] = __builtin_amdgcn_rcpf((lp[0] + lp[32]) + (lp[64] + lp[96])); }
;   float* Ow = Ob + (long)(g * 32) * LDO + kh * 128;
;   if (MODE == 0) {
; #pragma unroll
;     for (int r = 0; r < 16; ++r) { const int orow = crow(r, hi);
; #pragma unroll
;       for (int d0 = 0; d0 < 4; ++d0) Ow[(long)orow * LDO + d0 * 32 + r32] = o[d0][r] * rli[r]; }
;     asm volatile("s_waitcnt vmcnt(0)" ::: "memory"); __syncthreads();
	v_add_f32_e32 v1, v24, v28
	v_add_f32_e32 v0, v0, v1
	v_rcp_f32_e32 v8, v0
	v_add_f32_e32 v0, v17, v21
	v_add_f32_e32 v1, v25, v29
	v_add_f32_e32 v0, v0, v1
	v_rcp_f32_e32 v9, v0
	v_add_f32_e32 v0, v18, v22
	v_add_f32_e32 v1, v26, v30
	v_add_f32_e32 v0, v0, v1
	v_rcp_f32_e32 v10, v0
	v_add_f32_e32 v0, v19, v23
	v_add_f32_e32 v1, v27, v31
	v_add_f32_e32 v0, v0, v1
	v_rcp_f32_e32 v11, v0
	v_lshlrev_b64 v[0:1], 13, v[196:197]
	v_lshl_add_u64 v[0:1], s[28:29], 0, v[0:1]
	v_lshlrev_b32_e32 v194, 9, v211
	v_lshl_add_u64 v[0:1], v[0:1], 0, v[194:195]
	v_lshlrev_b32_e32 v194, 2, v206
	v_lshlrev_b32_e32 v2, 15, v207
	v_lshl_add_u64 v[0:1], v[0:1], 0, v[194:195]
	v_mov_b32_e32 v3, v195
	v_lshl_add_u64 v[0:1], v[0:1], 0, v[2:3]
	v_mul_f32_e32 v2, v64, v97
	global_store_dword v[0:1], v2, off
	v_mul_f32_e32 v2, v48, v97
	global_store_dword v[0:1], v2, off offset:128
	v_mul_f32_e32 v2, v32, v97
	global_store_dword v[0:1], v2, off offset:256
	v_mul_f32_e32 v2, v81, v97
	global_store_dword v[0:1], v2, off offset:384
	v_add_co_u32_e32 v2, vcc, s57, v0
	v_mul_f32_e32 v12, v65, v98
	s_nop 0
	v_addc_co_u32_e32 v3, vcc, 0, v1, vcc
	global_store_dword v[2:3], v12, off
	v_mul_f32_e32 v12, v49, v98
	global_store_dword v[2:3], v12, off offset:128
	v_mul_f32_e32 v12, v33, v98
	global_store_dword v[2:3], v12, off offset:256
	v_mul_f32_e32 v12, v82, v98
	global_store_dword v[2:3], v12, off offset:384
	v_add_co_u32_e32 v2, vcc, s62, v0
	v_mul_f32_e32 v12, v66, v99
	s_nop 0
	v_addc_co_u32_e32 v3, vcc, 0, v1, vcc
	global_store_dword v[2:3], v12, off
	v_mul_f32_e32 v12, v50, v99
	global_store_dword v[2:3], v12, off offset:128
	v_mul_f32_e32 v12, v34, v99
	global_store_dword v[2:3], v12, off offset:256
	v_mul_f32_e32 v12, v83, v99
	global_store_dword v[2:3], v12, off offset:384
	v_add_co_u32_e32 v2, vcc, s66, v0
	v_mul_f32_e32 v12, v67, v100
	s_nop 0
	v_addc_co_u32_e32 v3, vcc, 0, v1, vcc
	global_store_dword v[2:3], v12, off
	v_mul_f32_e32 v12, v51, v100
	global_store_dword v[2:3], v12, off offset:128
	v_mul_f32_e32 v12, v35, v100
	global_store_dword v[2:3], v12, off offset:256
	v_mul_f32_e32 v12, v84, v100
	global_store_dword v[2:3], v12, off offset:384
	v_add_co_u32_e32 v2, vcc, s64, v0
	v_mul_f32_e32 v12, v68, v101
	s_nop 0
	v_addc_co_u32_e32 v3, vcc, 0, v1, vcc
	global_store_dword v[2:3], v12, off
	v_mul_f32_e32 v12, v52, v101
	global_store_dword v[2:3], v12, off offset:128
	v_mul_f32_e32 v12, v36, v101
	global_store_dword v[2:3], v12, off offset:256
	v_mul_f32_e32 v12, v85, v101
	global_store_dword v[2:3], v12, off offset:384
	v_add_co_u32_e32 v2, vcc, s67, v0
	v_mul_f32_e32 v12, v69, v102
	s_nop 0
	v_addc_co_u32_e32 v3, vcc, 0, v1, vcc
	global_store_dword v[2:3], v12, off
	v_mul_f32_e32 v12, v53, v102
	global_store_dword v[2:3], v12, off offset:128
	v_mul_f32_e32 v12, v37, v102
	global_store_dword v[2:3], v12, off offset:256
	v_mul_f32_e32 v12, v86, v102
	global_store_dword v[2:3], v12, off offset:384
	v_add_co_u32_e32 v2, vcc, s68, v0
	v_mul_f32_e32 v12, v70, v103
	s_nop 0
	v_addc_co_u32_e32 v3, vcc, 0, v1, vcc
	global_store_dword v[2:3], v12, off
	v_mul_f32_e32 v12, v54, v103
	global_store_dword v[2:3], v12, off offset:128
	v_mul_f32_e32 v12, v38, v103
	global_store_dword v[2:3], v12, off offset:256
	v_mul_f32_e32 v12, v87, v103
	global_store_dword v[2:3], v12, off offset:384
	v_add_co_u32_e32 v2, vcc, s69, v0
	v_mul_f32_e32 v12, v71, v104
	s_nop 0
	v_addc_co_u32_e32 v3, vcc, 0, v1, vcc
	global_store_dword v[2:3], v12, off
	v_mul_f32_e32 v12, v55, v104
	global_store_dword v[2:3], v12, off offset:128
	v_mul_f32_e32 v12, v39, v104
	global_store_dword v[2:3], v12, off offset:256
	v_mul_f32_e32 v12, v88, v104
	global_store_dword v[2:3], v12, off offset:384
	v_add_co_u32_e32 v2, vcc, s63, v0
	v_mul_f32_e32 v12, v56, v4
	s_nop 0
	v_addc_co_u32_e32 v3, vcc, 0, v1, vcc
	global_store_dword v[2:3], v12, off
	v_mul_f32_e32 v12, v40, v4
	global_store_dword v[2:3], v12, off offset:128
	v_mul_f32_e32 v12, v72, v4
	v_mul_f32_e32 v4, v80, v4
	global_store_dword v[2:3], v12, off offset:256
	global_store_dword v[2:3], v4, off offset:384
	v_add_co_u32_e32 v2, vcc, s70, v0
	v_mul_f32_e32 v4, v57, v5
	s_nop 0
	v_addc_co_u32_e32 v3, vcc, 0, v1, vcc
	global_store_dword v[2:3], v4, off
	v_mul_f32_e32 v4, v41, v5
	global_store_dword v[2:3], v4, off offset:128
	v_mul_f32_e32 v4, v73, v5
	global_store_dword v[2:3], v4, off offset:256
	v_mul_f32_e32 v4, v89, v5
	global_store_dword v[2:3], v4, off offset:384
	v_add_co_u32_e32 v2, vcc, s71, v0
	v_mul_f32_e32 v4, v58, v6
	s_nop 0
	v_addc_co_u32_e32 v3, vcc, 0, v1, vcc
	global_store_dword v[2:3], v4, off
	v_mul_f32_e32 v4, v42, v6
	global_store_dword v[2:3], v4, off offset:128
	v_mul_f32_e32 v4, v74, v6
	global_store_dword v[2:3], v4, off offset:256
	v_mul_f32_e32 v4, v90, v6
	global_store_dword v[2:3], v4, off offset:384
	v_add_co_u32_e32 v2, vcc, s72, v0
	v_mul_f32_e32 v4, v59, v7
	s_nop 0
	v_addc_co_u32_e32 v3, vcc, 0, v1, vcc
	global_store_dword v[2:3], v4, off
	v_mul_f32_e32 v4, v43, v7
	global_store_dword v[2:3], v4, off offset:128
	v_mul_f32_e32 v4, v75, v7
	global_store_dword v[2:3], v4, off offset:256
	v_mul_f32_e32 v4, v91, v7
	global_store_dword v[2:3], v4, off offset:384
	v_add_co_u32_e32 v2, vcc, s73, v0
	v_mul_f32_e32 v4, v60, v8
	s_nop 0
	v_addc_co_u32_e32 v3, vcc, 0, v1, vcc
	global_store_dword v[2:3], v4, off
	v_mul_f32_e32 v4, v44, v8
	global_store_dword v[2:3], v4, off offset:128
	v_mul_f32_e32 v4, v76, v8
	global_store_dword v[2:3], v4, off offset:256
	v_mul_f32_e32 v4, v92, v8
	global_store_dword v[2:3], v4, off offset:384
	v_add_co_u32_e32 v2, vcc, s74, v0
	v_mul_f32_e32 v4, v61, v9
	s_nop 0
	v_addc_co_u32_e32 v3, vcc, 0, v1, vcc
	global_store_dword v[2:3], v4, off
	v_mul_f32_e32 v4, v45, v9
	global_store_dword v[2:3], v4, off offset:128
	v_mul_f32_e32 v4, v77, v9
	global_store_dword v[2:3], v4, off offset:256
	v_mul_f32_e32 v4, v93, v9
	global_store_dword v[2:3], v4, off offset:384
	v_add_co_u32_e32 v2, vcc, s75, v0
	v_mul_f32_e32 v4, v62, v10
	s_nop 0
	v_addc_co_u32_e32 v3, vcc, 0, v1, vcc
	global_store_dword v[2:3], v4, off
	v_mul_f32_e32 v4, v46, v10
	global_store_dword v[2:3], v4, off offset:128
	v_mul_f32_e32 v4, v78, v10
	global_store_dword v[2:3], v4, off offset:256
	v_mul_f32_e32 v4, v94, v10
	v_add_co_u32_e32 v0, vcc, s76, v0
	global_store_dword v[2:3], v4, off offset:384
	v_mul_f32_e32 v2, v63, v11
	v_addc_co_u32_e32 v1, vcc, 0, v1, vcc
	global_store_dword v[0:1], v2, off
	v_mul_f32_e32 v2, v47, v11
	global_store_dword v[0:1], v2, off offset:128
	v_mul_f32_e32 v2, v79, v11
	global_store_dword v[0:1], v2, off offset:256
	v_mul_f32_e32 v2, v95, v11
	global_store_dword v[0:1], v2, off offset:384
	v_mov_b32_e32 v194, v224
	s_nop 0
	s_waitcnt vmcnt(63) expcnt(7) lgkmcnt(15)
	s_barrier
; __device__ __forceinline__ int v_rd_base(int lane) { return ((lane & 3) << 3) | (((lane >> 2) & 3) << 6) | (((lane >> 4) & 1) << 5) | (((lane >> 5) & 1) << 8); }
; #define RAWBAR() do { asm volatile("s_waitcnt lgkmcnt(0)" ::: "memory"); __builtin_amdgcn_s_barrier(); asm volatile("" ::: "memory"); } while (0)
; #define RAWBAR() do { asm volatile("s_waitcnt lgkmcnt(0)" ::: "memory"); __builtin_amdgcn_s_barrier(); asm volatile("" ::: "memory"); } while (0)
; #define RAWBAR() do { asm volatile("s_waitcnt lgkmcnt(0)" ::: "memory"); __builtin_amdgcn_s_barrier(); asm volatile("" ::: "memory"); } while (0)
; #define RAWBAR() do { asm volatile("s_waitcnt lgkmcnt(0)" ::: "memory"); __builtin_amdgcn_s_barrier(); asm volatile("" ::: "memory"); } while (0)
; #define RAWBAR() do { asm volatile("s_waitcnt lgkmcnt(0)" ::: "memory"); __builtin_amdgcn_s_barrier(); asm volatile("" ::: "memory"); } while (0)
; #define RAWBAR() do { asm volatile("s_waitcnt lgkmcnt(0)" ::: "memory"); __builtin_amdgcn_s_barrier(); asm volatile("" ::: "memory"); } while (0)
; template <int MODE> ...
;     ...
;   const bf16* Qw = Qb + (long)(g * 32 + r32) * 128 + hi * 8;
; #pragma unroll
;   for (int d0 = 0; d0 < 8; ++d0) qr[d0] = St::ld8(Qw + d0 * 16);
;   const int vb0 = (int)(uintptr_t)V_lds + v_rd_base(lane) + 2 * kh * 4096;
;   const int krow = 32 * kh + r32;
;   typedef __attribute__((address_space(3))) unsigned lds_u32;
;   const int wu = __builtin_amdgcn_readfirstlane(wid);
;   long gk[2], gv[2];
; #pragma unroll
;   for (int c = 0; c < 2; ++c) { const int q = wu + 8 * c;
;     const int r = 4 * q + (lane >> 4), pch = lane & 15; gk[c] = (long)r * 128 + ((pch ^ (r & 7)) * 8);
;     const int st = 2 * q + (lane >> 5), kk = (st >> 2) * 8 + ((lane >> 2) & 7), k = (kk & ~0xC) | ((kk & 4) << 1) | ((kk & 8) >> 1), cc = (st & 3) * 32 + (lane & 3) * 8;
;     gv[c] = (long)k * 256 + cc; }
;     ...
;   const int NT = seq / KVBLK;
;   STAGE(0, 0); asm volatile("s_waitcnt vmcnt(0)" ::: "memory"); RAWBAR();
	v_mov_b32_e32 v199, v195
	v_ashrrev_i32_e32 v217, 7, v194
	v_and_b32_e32 v214, 31, v194
	v_lshlrev_b32_e32 v196, 5, v217
	v_or_b32_e32 v0, v196, v214
	v_ashrrev_i32_e32 v1, 31, v0
	v_bfe_u32 v213, v194, 5, 1
	v_lshlrev_b64 v[0:1], 8, v[0:1]
	v_lshl_add_u64 v[0:1], s[34:35], 0, v[0:1]
	v_lshlrev_b32_e32 v198, 4, v213
	v_lshl_add_u64 v[0:1], v[0:1], 0, v[198:199]
	v_lshl_add_u64 v[2:3], v[0:1], 0, s[20:21]
	v_add_co_u32_e32 v0, vcc, s77, v0
	v_ashrrev_i32_e32 v215, 6, v194
	s_add_u32 s36, s36, 0x410000
	v_addc_co_u32_e32 v1, vcc, 0, v1, vcc
	v_readfirstlane_b32 s2, v215
	s_addc_u32 s37, s37, 0
	global_load_dwordx4 v[184:187], v[2:3], off offset:32
	global_load_dwordx4 v[180:183], v[2:3], off offset:64
	global_load_dwordx4 v[176:179], v[2:3], off offset:96
	global_load_dwordx4 v[172:175], v[2:3], off offset:128
	global_load_dwordx4 v[168:171], v[2:3], off offset:160
	global_load_dwordx4 v[164:167], v[2:3], off offset:192
	global_load_dwordx4 v[188:191], v[0:1], off
	global_load_dwordx4 v[160:163], v[2:3], off offset:224
	v_bfe_u32 v199, v194, 4, 2
	v_bfe_u32 v0, v194, 2, 2
	v_lshrrev_b32_e32 v1, 1, v194
	s_lshl_b32 s3, s2, 2
	s_lshl_b32 s34, s2, 1
	v_and_or_b32 v6, v1, 8, v0
	v_or_b32_e32 v0, s3, v199
	s_and_b32 s3, s3, -16
	s_and_b32 s35, s34, 4
	s_or_b32 s3, s3, s35
	v_or_b32_e32 v2, s3, v6
	s_add_i32 s3, s2, 8
	v_and_b32_e32 v4, 63, v194
	v_and_or_b32 v14, s34, 2, v213
	s_lshl_b32 s34, s3, 2
	s_lshl_b32 s35, s3, 1
	v_lshlrev_b32_e32 v8, 3, v4
	v_lshlrev_b32_e32 v197, 4, v4
	v_or_b32_e32 v4, s34, v199
	s_and_b32 s34, s34, -16
	s_and_b32 s41, s35, 4
	v_lshlrev_b32_e32 v9, 1, v194
	v_and_b32_e32 v211, 15, v194
	v_ashrrev_i32_e32 v1, 31, v0
	s_or_b32 s34, s34, s41
	v_and_b32_e32 v12, 0x100, v8
	v_bitop3_b32 v10, v0, v211, 7 bitop3:0x6c
	v_ashrrev_i32_e32 v5, 31, v4
	v_bitop3_b32 v15, v4, v211, 7 bitop3:0x6c
	v_or_b32_e32 v6, s34, v6
	v_and_b32_e32 v17, 24, v8
	v_and_b32_e32 v19, 32, v9
	v_lshlrev_b64 v[8:9], 8, v[0:1]
	s_lshl_b32 s34, s2, 10
	v_lshlrev_b32_e32 v212, 3, v194
	v_and_or_b32 v16, s35, 2, v213
	v_lshl_or_b32 v8, v10, 4, v8
	s_add_i32 s35, s34, 0
	v_lshlrev_b64 v[4:5], 8, v[4:5]
	v_lshlrev_b32_e32 v15, 4, v15
	v_and_b32_e32 v13, 24, v212
	v_ashrrev_i32_e32 v3, 31, v2
	v_lshl_add_u64 v[10:11], s[36:37], 0, v[8:9]
	s_mov_b32 m0, s35
	v_or_b32_e32 v4, v4, v15
	v_ashrrev_i32_e32 v7, 31, v6
	global_load_lds_dwordx4 v[10:11], off
	v_lshl_add_u64 v[128:129], v[10:11], 0, s[18:19]
	v_lshl_add_u64 v[4:5], s[36:37], 0, v[4:5]
	v_lshl_add_u64 v[130:131], v[4:5], 0, s[18:19]
	s_add_i32 m0, s35, 0x2000
	v_lshlrev_b32_e32 v1, 6, v14
	v_lshlrev_b32_e32 v10, 1, v13
	v_lshlrev_b64 v[2:3], 9, v[2:3]
	global_load_lds_dwordx4 v[4:5], off
	s_add_i32 m0, s35, 0x4000
	s_nop 0
	global_load_lds_dwordx4 v[128:129], off
	s_add_i32 m0, s35, 0x6000
	s_nop 0
	global_load_lds_dwordx4 v[130:131], off
	v_or3_b32 v4, v1, v10, v2
	v_lshrrev_b32_e32 v132, 11, v4
	v_lshrrev_b32_e32 v133, 12, v4
	v_xor_b32_e32 v132, v132, v133
	v_and_b32_e32 v132, 1, v132
	v_mul_u32_u24_e32 v132, 0x1800, v132
	v_xor_b32_e32 v4, v4, v132
	v_mov_b32_e32 v5, v3
	v_lshlrev_b32_e32 v1, 6, v16
	v_lshlrev_b64 v[6:7], 9, v[6:7]
	v_lshl_add_u64 v[4:5], s[30:31], 0, v[4:5]
	s_add_i32 m0, s35, 0x8000
	v_or3_b32 v10, v1, v10, v6
	v_lshrrev_b32_e32 v132, 11, v10
	v_lshrrev_b32_e32 v133, 12, v10
	v_xor_b32_e32 v132, v132, v133
	v_and_b32_e32 v132, 1, v132
	v_mul_u32_u24_e32 v132, 0x1800, v132
	v_xor_b32_e32 v10, v10, v132
	v_mov_b32_e32 v11, v7
	global_load_lds_dwordx4 v[4:5], off
	v_lshl_add_u64 v[10:11], s[30:31], 0, v[10:11]
	s_add_i32 m0, s35, 0xa000
	v_lshl_add_u64 v[4:5], v[4:5], 0, s[10:11]
	global_load_lds_dwordx4 v[10:11], off
	s_add_i32 m0, s35, 0xc000
	v_and_b32_e32 v216, 1, v215
	global_load_lds_dwordx4 v[4:5], off
	v_lshl_add_u64 v[4:5], v[10:11], 0, s[10:11]
	s_add_i32 m0, s35, 0xe000
	v_lshlrev_b32_e32 v20, 13, v216
	global_load_lds_dwordx4 v[4:5], off
	s_cmp_lg_u32 s33, -1
	v_lshl_or_b32 v1, v214, 8, v20
	s_cselect_b32 s30, s33, 0
	s_and_b32 s2, s2, 1
	v_lshlrev_b32_e32 v4, 4, v194
	v_add_u32_e32 v220, 0, v1
	s_lshl_b32 s2, s2, 6
	v_and_b32_e32 v1, 32, v194
	v_and_b32_e32 v5, 0x70, v4
	v_bitop3_b32 v229, v198, v4, s58 bitop3:0x78
	v_or3_b32 v4, s2, v1, v13
	s_and_b32 s2, s3, 1
	s_lshl_b32 s2, s2, 6
	v_or3_b32 v1, s2, v1, v13
	v_add_u32_e32 v0, 32, v0
	v_and_b32_e32 v18, 0xc0, v197
	s_waitcnt vmcnt(0)
	v_lshl_or_b32 v6, v1, 1, v6
	v_ashrrev_i32_e32 v1, 31, v0
	s_waitcnt lgkmcnt(0)
	s_barrier
; __device__ __forceinline__ int v_rd_base(int lane) { return ((lane & 3) << 3) | (((lane >> 2) & 3) << 6) | (((lane >> 4) & 1) << 5) | (((lane >> 5) & 1) << 8); }
; #define RAWBAR() do { asm volatile("s_waitcnt lgkmcnt(0)" ::: "memory"); __builtin_amdgcn_s_barrier(); asm volatile("" ::: "memory"); } while (0)
; #define RAWBAR() do { asm volatile("s_waitcnt lgkmcnt(0)" ::: "memory"); __builtin_amdgcn_s_barrier(); asm volatile("" ::: "memory"); } while (0)
; #define RAWBAR() do { asm volatile("s_waitcnt lgkmcnt(0)" ::: "memory"); __builtin_amdgcn_s_barrier(); asm volatile("" ::: "memory"); } while (0)
; template <int MODE> ...
;     ...
;   f32x16 o[8] = {}; bf16x8 qr[8]; float lsum = 0.f;
;   const bf16* Qw = Qb + (long)(g * 32 + r32) * 128 + hi * 8;
; #pragma unroll
;   for (int d0 = 0; d0 < 8; ++d0) qr[d0] = St::ld8(Qw + d0 * 16);
;   const int vb0 = (int)(uintptr_t)V_lds + v_rd_base(lane) + 2 * kh * 4096;
;   const int krow = 32 * kh + r32;
;   typedef __attribute__((address_space(3))) unsigned lds_u32;
;   const int wu = __builtin_amdgcn_readfirstlane(wid);
;   long gk[2], gv[2];
; #pragma unroll
;   for (int c = 0; c < 2; ++c) { const int q = wu + 8 * c;
;     const int r = 4 * q + (lane >> 4), pch = lane & 15; gk[c] = (long)r * 128 + ((pch ^ (r & 7)) * 8);
;     const int st = 2 * q + (lane >> 5), kk = (st >> 2) * 8 + ((lane >> 2) & 7), k = (kk & ~0xC) | ((kk & 4) << 1) | ((kk & 8) >> 1), cc = (st & 3) * 32 + (lane & 3) * 8;
;     gv[c] = (long)k * 256 + cc; }
;     ...
;   const int NT = seq / KVBLK;
;   STAGE(0, 0); asm volatile("s_waitcnt vmcnt(0)" ::: "memory"); RAWBAR();
;   if (false) __builtin_amdgcn_s_setprio(1);
;   for (int j = 0; j < NT; ++j) {
;     const int buf = j & 1;
;     if (j + 1 < NT) { STAGE((j + 1) * KVBLK, buf ^ 1); }
;     const char* Kb = K_lds + buf * 16384;
;     f32x16 pe = {}, po = {};
; #pragma unroll
;     for (int d0 = 0; d0 < 8; d0 += 2) {
;       const bf16x8 k0 = *reinterpret_cast<const bf16x8*>(Kb + KSWZ(krow, (d0 * 16 + hi * 8) * 2));
;       const bf16x8 k1 = *reinterpret_cast<const bf16x8*>(Kb + KSWZ(krow, ((d0 + 1) * 16 + hi * 8) * 2));
;       pe = __builtin_amdgcn_mfma_f32_32x32x16_bf16(k0, qr[d0], pe, 0, 0, 0);
;       po = __builtin_amdgcn_mfma_f32_32x32x16_bf16(k1, qr[d0 + 1], po, 0, 0, 0); }
	v_add_u32_e32 v10, s30, v18
	v_readlane_b32 s84, v251, 28
	v_lshlrev_b64 v[0:1], 8, v[0:1]
	v_add3_u32 v10, v10, v17, v19
	v_lshl_or_b32 v2, v4, 1, v2
	v_readlane_b32 s85, v251, 29
	v_or_b32_e32 v0, v0, v15
	v_mov_b32_e32 v219, 0
	s_mov_b32 s40, 0
	v_add3_u32 v218, v10, v12, v20
	v_bitop3_b32 v228, v198, v5, 32 bitop3:0x36
	v_bitop3_b32 v227, v198, v5, 64 bitop3:0x36
	v_bitop3_b32 v226, v198, v5, s43 bitop3:0x36
	v_bitop3_b32 v225, v198, v5, s59 bitop3:0x36
	v_bitop3_b32 v223, v198, v5, s60 bitop3:0x36
	v_bitop3_b32 v222, v198, v5, s56 bitop3:0x36
	v_bitop3_b32 v221, v198, v5, s61 bitop3:0x36
	v_lshl_add_u64 v[200:201], s[84:85], 0, v[2:3]
	v_lshl_add_u64 v[202:203], s[84:85], 0, v[6:7]
	v_lshl_add_u64 v[204:205], s[8:9], 0, v[8:9]
	v_lshl_add_u64 v[206:207], s[8:9], 0, v[0:1]
	v_mov_b32_e32 v0, 0
	v_mov_b32_e32 v1, v219
	v_mov_b32_e32 v2, v219
	v_mov_b32_e32 v3, v219
	v_mov_b32_e32 v4, v219
	v_mov_b32_e32 v5, v219
	v_mov_b32_e32 v6, v219
	v_mov_b32_e32 v7, v219
	v_mov_b32_e32 v8, v219
	v_mov_b32_e32 v9, v219
	v_mov_b32_e32 v10, v219
	v_mov_b32_e32 v11, v219
	v_mov_b32_e32 v12, v219
	v_mov_b32_e32 v13, v219
	v_mov_b32_e32 v14, v219
	v_mov_b32_e32 v15, v219
	v_mov_b32_e32 v48, 0
	v_mov_b32_e32 v49, v219
	v_mov_b32_e32 v50, v219
	v_mov_b32_e32 v51, v219
	v_mov_b32_e32 v52, v219
	v_mov_b32_e32 v53, v219
	v_mov_b32_e32 v54, v219
	v_mov_b32_e32 v55, v219
	v_mov_b32_e32 v56, v219
	v_mov_b32_e32 v57, v219
	v_mov_b32_e32 v58, v219
	v_mov_b32_e32 v59, v219
	v_mov_b32_e32 v60, v219
	v_mov_b32_e32 v61, v219
	v_mov_b32_e32 v62, v219
	v_mov_b32_e32 v63, v219
	v_mov_b32_e32 v16, 0
	v_mov_b32_e32 v17, v219
	v_mov_b32_e32 v18, v219
	v_mov_b32_e32 v19, v219
	v_mov_b32_e32 v20, v219
	v_mov_b32_e32 v21, v219
	v_mov_b32_e32 v22, v219
	v_mov_b32_e32 v23, v219
	v_mov_b32_e32 v24, v219
	v_mov_b32_e32 v25, v219
	v_mov_b32_e32 v26, v219
	v_mov_b32_e32 v27, v219
	v_mov_b32_e32 v28, v219
	v_mov_b32_e32 v29, v219
	v_mov_b32_e32 v30, v219
	v_mov_b32_e32 v31, v219
	v_mov_b32_e32 v32, 0
	v_mov_b32_e32 v33, v219
	v_mov_b32_e32 v34, v219
	v_mov_b32_e32 v35, v219
	v_mov_b32_e32 v36, v219
	v_mov_b32_e32 v37, v219
	v_mov_b32_e32 v38, v219
	v_mov_b32_e32 v39, v219
	v_mov_b32_e32 v40, v219
	v_mov_b32_e32 v41, v219
	v_mov_b32_e32 v42, v219
	v_mov_b32_e32 v43, v219
	v_mov_b32_e32 v44, v219
	v_mov_b32_e32 v45, v219
	v_mov_b32_e32 v46, v219
	v_mov_b32_e32 v47, v219
	v_mov_b32_e32 v64, 0
	v_mov_b32_e32 v65, v219
	v_mov_b32_e32 v66, v219
	v_mov_b32_e32 v67, v219
	v_mov_b32_e32 v68, v219
	v_mov_b32_e32 v69, v219
	v_mov_b32_e32 v70, v219
	v_mov_b32_e32 v71, v219
	v_mov_b32_e32 v72, v219
	v_mov_b32_e32 v73, v219
	v_mov_b32_e32 v74, v219
	v_mov_b32_e32 v75, v219
	v_mov_b32_e32 v76, v219
	v_mov_b32_e32 v77, v219
	v_mov_b32_e32 v78, v219
	v_mov_b32_e32 v79, v219
	v_mov_b32_e32 v80, 0
	v_mov_b32_e32 v81, v219
	v_mov_b32_e32 v82, v219
	v_mov_b32_e32 v83, v219
	v_mov_b32_e32 v84, v219
	v_mov_b32_e32 v85, v219
	v_mov_b32_e32 v86, v219
	v_mov_b32_e32 v87, v219
	v_mov_b32_e32 v88, v219
	v_mov_b32_e32 v89, v219
	v_mov_b32_e32 v90, v219
	v_mov_b32_e32 v91, v219
	v_mov_b32_e32 v92, v219
	v_mov_b32_e32 v93, v219
	v_mov_b32_e32 v94, v219
	v_mov_b32_e32 v95, v219
	v_mov_b32_e32 v96, 0
	v_mov_b32_e32 v97, v219
	v_mov_b32_e32 v98, v219
	v_mov_b32_e32 v99, v219
	v_mov_b32_e32 v100, v219
	v_mov_b32_e32 v101, v219
	v_mov_b32_e32 v102, v219
	v_mov_b32_e32 v103, v219
	v_mov_b32_e32 v104, v219
	v_mov_b32_e32 v105, v219
	v_mov_b32_e32 v106, v219
	v_mov_b32_e32 v107, v219
	v_mov_b32_e32 v108, v219
	v_mov_b32_e32 v109, v219
	v_mov_b32_e32 v110, v219
	v_mov_b32_e32 v111, v219
	v_mov_b32_e32 v112, 0
	v_mov_b32_e32 v113, v219
	v_mov_b32_e32 v114, v219
	v_mov_b32_e32 v115, v219
	v_mov_b32_e32 v116, v219
	v_mov_b32_e32 v117, v219
	v_mov_b32_e32 v118, v219
	v_mov_b32_e32 v119, v219
	v_mov_b32_e32 v120, v219
	v_mov_b32_e32 v121, v219
	v_mov_b32_e32 v122, v219
	v_mov_b32_e32 v123, v219
	v_mov_b32_e32 v124, v219
	v_mov_b32_e32 v125, v219
	v_mov_b32_e32 v126, v219
	v_mov_b32_e32 v127, v219
	v_readlane_b32 s86, v251, 30
	v_readlane_b32 s87, v251, 31
	s_waitcnt vmcnt(0)
	v_subrev_u32_e32 v225, s8, v204
	v_subrev_u32_e32 v223, s8, v206
	v_subrev_u32_e32 v222, s84, v200
	v_subrev_u32_e32 v221, s84, v202
	v_lshrrev_b32_e32 v246, 11, v222
	v_lshrrev_b32_e32 v247, 12, v222
	v_xor_b32_e32 v246, v246, v247
	v_and_b32_e32 v246, 1, v246
	v_mul_u32_u24_e32 v246, 0x1800, v246
	v_xor_b32_e32 v222, v222, v246
	v_lshrrev_b32_e32 v246, 11, v221
	v_lshrrev_b32_e32 v247, 12, v221
	v_xor_b32_e32 v246, v246, v247
	v_and_b32_e32 v246, 1, v246
	v_mul_u32_u24_e32 v246, 0x1800, v246
	v_xor_b32_e32 v221, v221, v246
	v_add_u32_e32 v246, 0x100, v222
	v_add_u32_e32 v247, 0x100, v221
	s_add_u32 s86, s8, s26
	s_addc_u32 s87, s9, s27
	s_add_u32 s86, s86, 0x4000
	s_addc_u32 s87, s87, 0
	s_add_u32 s2, s84, s26
	s_addc_u32 s3, s85, s27
	s_add_u32 s2, s2, s12
	s_addc_u32 s3, s3, s13
	v_add_u32_e32 v229, v220, v229
	v_add_u32_e32 v228, v220, v228
	v_add_u32_e32 v227, v220, v227
	v_add_u32_e32 v226, v220, v226
	ds_read_b128 v[230:233], v229 offset:0
	ds_read_b128 v[234:237], v228 offset:0
	s_waitcnt lgkmcnt(0)
	v_mfma_f32_32x32x16_bf16 v[144:159], v[230:233], v[188:191], 0
	v_mfma_f32_32x32x16_bf16 v[144:159], v[234:237], v[184:187], v[144:159]
	ds_read_b128 v[230:233], v227 offset:0
	ds_read_b128 v[234:237], v226 offset:0
	s_waitcnt lgkmcnt(0)
	v_mfma_f32_32x32x16_bf16 v[144:159], v[230:233], v[180:183], v[144:159]
	v_mfma_f32_32x32x16_bf16 v[144:159], v[234:237], v[176:179], v[144:159]
	ds_read_b128 v[230:233], v229 offset:128
	ds_read_b128 v[234:237], v228 offset:128
	s_waitcnt lgkmcnt(0)
	v_mfma_f32_32x32x16_bf16 v[144:159], v[230:233], v[172:175], v[144:159]
	v_mfma_f32_32x32x16_bf16 v[144:159], v[234:237], v[168:171], v[144:159]
	ds_read_b128 v[230:233], v227 offset:128
	ds_read_b128 v[234:237], v226 offset:128
	s_waitcnt lgkmcnt(0)
	v_mfma_f32_32x32x16_bf16 v[144:159], v[230:233], v[164:167], v[144:159]
	v_mfma_f32_32x32x16_bf16 v[144:159], v[234:237], v[160:163], v[144:159]
	s_mov_b32 s84, 0
	s_barrier
	s_cmp_lt_u32 s34, 0x1000
	s_cbranch_scc0 .LattnBpre_m1
